# all 13 hoisted blocks: split-K fix-up / final norm / mLSTM / mixer loads issued at block top plus rope-lookup address re-materialisation
# speedup vs baseline: 1.0043x; 1.0043x over previous
.LBB0_153:
	s_ashr_i32 s7, s12, 10
	s_add_i32 s7, s7, 1
	s_and_b64 s[12:13], s[4:5], exec
	s_cselect_b32 s7, s7, 0
	s_and_b64 s[14:15], s[10:11], s[4:5]
	v_cndmask_b32_e64 v34, 0, 1, s[14:15]
	s_mul_hi_i32 s13, s7, 0x3000
	v_cmp_ne_u32_e64 s[4:5], 1, v34
	s_andn2_b64 vcc, exec, s[14:15]
	s_mul_i32 s12, s7, 0x3000
	s_cbranch_vccnz .LBB0_155
	s_lshl_b64 s[14:15], s[46:47], 12
	v_lshl_add_u64 v[70:71], v[138:139], 0, s[14:15]
	global_load_dwordx4 v[50:53], v[70:71], off
	s_mov_b32 s7, 0x800000
	v_add_co_u32_e32 v72, vcc, s7, v70
	s_mov_b32 s7, 0x1000000
	s_nop 0
	v_addc_co_u32_e32 v73, vcc, 0, v71, vcc
	global_load_dwordx4 v[54:57], v[72:73], off
	v_add_co_u32_e32 v74, vcc, s7, v70
	s_nop 0
	s_nop 0
	v_addc_co_u32_e32 v75, vcc, 0, v71, vcc
	global_load_dwordx4 v[58:61], v[74:75], off
	s_mov_b32 s7, 0x1800000
	v_add_co_u32_e32 v76, vcc, s7, v70
	s_lshl_b64 s[14:15], s[12:13], 2
	s_nop 0
	v_addc_co_u32_e32 v77, vcc, 0, v71, vcc
	global_load_dwordx4 v[62:65], v[76:77], off
	global_load_dwordx4 v[46:49], v[70:71], off offset:1024
	global_load_dwordx4 v[34:37], v[72:73], off offset:1024
	global_load_dwordx4 v[38:41], v[74:75], off offset:1024
	global_load_dwordx4 v[42:45], v[76:77], off offset:1024
	s_nop 0
	s_nop 0
	s_nop 0
	s_add_u32 s14, s8, s14
	s_addc_u32 s15, s9, s15
	global_load_dwordx4 v[82:85], v0, s[14:15]
	global_load_dwordx4 v[86:89], v0, s[14:15] offset:16
	global_load_dwordx4 v[90:93], v0, s[14:15] offset:2048
	global_load_dwordx4 v[94:97], v[76:77], off offset:2048
	global_load_dwordx4 v[98:101], v0, s[14:15] offset:2064
	global_load_dwordx4 v[102:105], v[70:71], off offset:2048
	global_load_dwordx4 v[106:109], v[72:73], off offset:2048
	global_load_dwordx4 v[110:113], v[74:75], off offset:2048
	global_load_dwordx4 v[114:117], v[70:71], off offset:3072
	global_load_dwordx4 v[118:121], v[72:73], off offset:3072
	s_nop 0
	s_waitcnt vmcnt(18)
	s_waitcnt vmcnt(17)
	v_and_b32_e32 v66, 0xffff0000, v50
	s_waitcnt vmcnt(16)
	v_and_b32_e32 v68, 0xffff0000, v54
	v_and_b32_e32 v78, 0xffff0000, v55
	v_lshlrev_b32_e32 v50, 16, v50
	s_waitcnt vmcnt(15)
	v_and_b32_e32 v67, 0xffff0000, v58
	v_lshlrev_b32_e32 v54, 16, v54
	s_waitcnt vmcnt(14)
	v_and_b32_e32 v69, 0xffff0000, v62
	v_pk_add_f32 v[66:67], v[66:67], v[68:69]
	v_and_b32_e32 v68, 0xffff0000, v51
	v_and_b32_e32 v69, 0xffff0000, v59
	v_and_b32_e32 v79, 0xffff0000, v63
	v_pk_add_f32 v[68:69], v[68:69], v[78:79]
	v_add_f32_e32 v78, v54, v50
	v_lshlrev_b32_e32 v50, 16, v58
	v_lshlrev_b32_e32 v54, 16, v62
	v_add_f32_e32 v80, v54, v50
	v_lshlrev_b32_e32 v50, 16, v51
	v_lshlrev_b32_e32 v51, 16, v55
	v_add_f32_e32 v50, v51, v50
	v_lshlrev_b32_e32 v51, 16, v59
	v_lshlrev_b32_e32 v54, 16, v63
	v_mov_b32_e32 v79, v66
	v_mov_b32_e32 v81, v67
	v_add_f32_e32 v54, v54, v51
	v_mov_b32_e32 v51, v68
	v_mov_b32_e32 v55, v69
	s_nop 0
	v_pk_add_f32 v[58:59], v[78:79], v[80:81]
	v_pk_add_f32 v[50:51], v[50:51], v[54:55]
	v_lshlrev_b32_e32 v62, 16, v60
	v_lshlrev_b32_e32 v63, 16, v57
	v_and_b32_e32 v54, 0xffff0000, v56
	v_and_b32_e32 v55, 0xffff0000, v64
	v_lshlrev_b32_e32 v64, 16, v64
	v_add_f32_e32 v62, v64, v62
	s_waitcnt vmcnt(11)
	v_lshlrev_b32_e32 v79, 16, v41
	v_lshlrev_b32_e32 v81, 16, v37
	v_lshlrev_b32_e32 v78, 16, v49
	s_waitcnt vmcnt(9)
	v_pk_fma_f32 v[30:31], v[82:83], v[58:59], v[30:31]
	v_pk_fma_f32 v[32:33], v[84:85], v[50:51], v[32:33]
	v_lshlrev_b32_e32 v58, 16, v52
	v_lshlrev_b32_e32 v59, 16, v53
	v_and_b32_e32 v50, 0xffff0000, v52
	v_and_b32_e32 v52, 0xffff0000, v53
	v_and_b32_e32 v51, 0xffff0000, v60
	v_and_b32_e32 v53, 0xffff0000, v61
	v_lshlrev_b32_e32 v60, 16, v56
	v_and_b32_e32 v56, 0xffff0000, v57
	v_and_b32_e32 v57, 0xffff0000, v65
	v_pk_add_f32 v[54:55], v[50:51], v[54:55]
	v_pk_add_f32 v[56:57], v[52:53], v[56:57]
	s_nop 0
	v_lshlrev_b32_e32 v61, 16, v61
	v_lshlrev_b32_e32 v65, 16, v65
	v_add_f32_e32 v58, v60, v58
	v_add_f32_e32 v60, v63, v59
	v_add_f32_e32 v64, v65, v61
	v_mov_b32_e32 v59, v54
	v_mov_b32_e32 v63, v55
	v_mov_b32_e32 v61, v56
	v_mov_b32_e32 v65, v57
	s_nop 0
	v_pk_add_f32 v[58:59], v[58:59], v[62:63]
	v_pk_add_f32 v[60:61], v[60:61], v[64:65]
	s_nop 0
	s_nop 0
	v_lshlrev_b32_e32 v80, 16, v45
	s_waitcnt vmcnt(8)
	v_pk_fma_f32 v[26:27], v[86:87], v[58:59], v[26:27]
	v_pk_fma_f32 v[28:29], v[88:89], v[60:61], v[28:29]
	v_and_b32_e32 v53, 0xffff0000, v38
	v_and_b32_e32 v52, 0xffff0000, v46
	v_and_b32_e32 v59, 0xffff0000, v42
	v_and_b32_e32 v58, 0xffff0000, v34
	v_lshlrev_b32_e32 v50, 16, v34
	v_pk_add_f32 v[52:53], v[52:53], v[58:59]
	v_and_b32_e32 v59, 0xffff0000, v39
	v_and_b32_e32 v58, 0xffff0000, v47
	v_and_b32_e32 v61, 0xffff0000, v43
	v_and_b32_e32 v60, 0xffff0000, v35
	v_lshlrev_b32_e32 v34, 16, v38
	v_lshlrev_b32_e32 v38, 16, v42
	v_pk_add_f32 v[58:59], v[58:59], v[60:61]
	v_add_f32_e32 v60, v38, v34
	v_lshlrev_b32_e32 v34, 16, v35
	v_lshlrev_b32_e32 v35, 16, v47
	v_lshlrev_b32_e32 v51, 16, v46
	v_add_f32_e32 v34, v34, v35
	v_lshlrev_b32_e32 v35, 16, v39
	v_lshlrev_b32_e32 v38, 16, v43
	v_add_f32_e32 v50, v50, v51
	v_mov_b32_e32 v51, v52
	v_mov_b32_e32 v61, v53
	v_add_f32_e32 v38, v38, v35
	v_mov_b32_e32 v35, v58
	v_mov_b32_e32 v39, v59
	v_pk_add_f32 v[46:47], v[50:51], v[60:61]
	v_pk_add_f32 v[34:35], v[34:35], v[38:39]
	s_waitcnt vmcnt(7)
	v_pk_fma_f32 v[22:23], v[90:91], v[46:47], v[22:23]
	s_nop 0
	v_pk_fma_f32 v[24:25], v[92:93], v[34:35], v[24:25]
	s_nop 0
	s_nop 0
	v_and_b32_e32 v34, 0xffff0000, v48
	v_lshlrev_b32_e32 v47, 16, v40
	v_and_b32_e32 v35, 0xffff0000, v40
	v_and_b32_e32 v39, 0xffff0000, v41
	v_and_b32_e32 v41, 0xffff0000, v44
	v_and_b32_e32 v40, 0xffff0000, v36
	v_lshlrev_b32_e32 v46, 16, v48
	v_lshlrev_b32_e32 v48, 16, v44
	v_lshlrev_b32_e32 v44, 16, v36
	v_pk_add_f32 v[34:35], v[34:35], v[40:41]
	v_and_b32_e32 v38, 0xffff0000, v49
	v_and_b32_e32 v43, 0xffff0000, v45
	v_and_b32_e32 v42, 0xffff0000, v37
	v_add_f32_e32 v36, v44, v46
	v_add_f32_e32 v40, v48, v47
	v_mov_b32_e32 v37, v34
	v_mov_b32_e32 v41, v35
	v_pk_add_f32 v[38:39], v[38:39], v[42:43]
	v_pk_add_f32 v[40:41], v[36:37], v[40:41]
	s_nop 0
	s_waitcnt vmcnt(5)
	v_pk_fma_f32 v[18:19], v[98:99], v[40:41], v[18:19]
	v_add_f32_e32 v66, v81, v78
	v_add_f32_e32 v70, v80, v79
	v_mov_b32_e32 v67, v38
	v_mov_b32_e32 v71, v39
	v_pk_add_f32 v[66:67], v[66:67], v[70:71]
	s_nop 0
	v_pk_fma_f32 v[20:21], v[100:101], v[66:67], v[20:21]
	global_load_dwordx4 v[42:45], v[74:75], off offset:3072
	global_load_dwordx4 v[38:41], v[76:77], off offset:3072
	global_load_dwordx4 v[122:125], v145, s[14:15]
	global_load_dwordx4 v[126:129], v145, s[14:15] offset:16
	global_load_dwordx4 v[150:153], v146, s[14:15]
	global_load_dwordx4 v[154:157], v146, s[14:15] offset:16
	v_and_b32_e32 v71, 0xffff0000, v94
	v_and_b32_e32 v73, 0xffff0000, v95
	s_nop 0
	v_lshlrev_b32_e32 v75, 16, v97
	s_waitcnt vmcnt(10)
	v_lshlrev_b32_e32 v67, 16, v102
	s_waitcnt vmcnt(9)
	v_lshlrev_b32_e32 v66, 16, v106
	v_add_f32_e32 v68, v66, v67
	s_waitcnt vmcnt(8)
	v_and_b32_e32 v67, 0xffff0000, v110
	v_and_b32_e32 v66, 0xffff0000, v102
	v_and_b32_e32 v70, 0xffff0000, v106
	v_pk_add_f32 v[70:71], v[66:67], v[70:71]
	v_and_b32_e32 v67, 0xffff0000, v111
	v_and_b32_e32 v66, 0xffff0000, v103
	v_and_b32_e32 v72, 0xffff0000, v107
	v_lshlrev_b32_e32 v50, 16, v110
	v_lshlrev_b32_e32 v54, 16, v94
	v_pk_add_f32 v[66:67], v[66:67], v[72:73]
	v_add_f32_e32 v72, v54, v50
	v_mov_b32_e32 v69, v70
	v_mov_b32_e32 v73, v71
	v_pk_add_f32 v[68:69], v[68:69], v[72:73]
	s_nop 0
	v_lshlrev_b32_e32 v50, 16, v107
	v_lshlrev_b32_e32 v103, 16, v103
	v_add_f32_e32 v50, v50, v103
	v_lshlrev_b32_e32 v51, 16, v111
	v_lshlrev_b32_e32 v54, 16, v95
	v_add_f32_e32 v54, v54, v51
	v_mov_b32_e32 v51, v66
	v_mov_b32_e32 v55, v67
	v_pk_add_f32 v[50:51], v[50:51], v[54:55]
	v_and_b32_e32 v54, 0xffff0000, v104
	v_and_b32_e32 v58, 0xffff0000, v105
	v_and_b32_e32 v55, 0xffff0000, v112
	v_and_b32_e32 v59, 0xffff0000, v113
	v_lshlrev_b32_e32 v74, 16, v113
	v_and_b32_e32 v61, 0xffff0000, v96
	v_and_b32_e32 v63, 0xffff0000, v97
	v_lshlrev_b32_e32 v65, 16, v109
	v_and_b32_e32 v62, 0xffff0000, v109
	v_pk_add_f32 v[58:59], v[58:59], v[62:63]
	s_waitcnt vmcnt(3)
	v_pk_fma_f32 v[14:15], v[122:123], v[68:69], v[14:15]
	s_nop 0
	v_pk_fma_f32 v[16:17], v[124:125], v[50:51], v[16:17]
	v_lshlrev_b32_e32 v70, 16, v104
	v_lshlrev_b32_e32 v71, 16, v105
	v_lshlrev_b32_e32 v72, 16, v112
	v_and_b32_e32 v60, 0xffff0000, v108
	s_nop 0
	v_lshlrev_b32_e32 v73, 16, v96
	v_lshlrev_b32_e32 v64, 16, v108
	v_pk_add_f32 v[60:61], v[54:55], v[60:61]
	s_nop 0
	v_add_f32_e32 v62, v64, v70
	v_add_f32_e32 v64, v73, v72
	v_add_f32_e32 v70, v65, v71
	v_add_f32_e32 v72, v75, v74
	v_mov_b32_e32 v63, v60
	v_mov_b32_e32 v65, v61
	v_mov_b32_e32 v71, v58
	v_mov_b32_e32 v73, v59
	v_pk_add_f32 v[60:61], v[62:63], v[64:65]
	v_pk_add_f32 v[58:59], v[70:71], v[72:73]
	v_and_b32_e32 v65, 0xffff0000, v38
	v_and_b32_e32 v64, 0xffff0000, v118
	v_and_b32_e32 v63, 0xffff0000, v42
	v_and_b32_e32 v62, 0xffff0000, v114
	v_pk_add_f32 v[62:63], v[62:63], v[64:65]
	s_waitcnt vmcnt(2)
	v_pk_fma_f32 v[10:11], v[126:127], v[60:61], v[10:11]
	v_pk_fma_f32 v[12:13], v[128:129], v[58:59], v[12:13]
	v_lshlrev_b32_e32 v58, 16, v118
	v_lshlrev_b32_e32 v59, 16, v114
	v_lshlrev_b32_e32 v60, 16, v38
	v_lshlrev_b32_e32 v34, 16, v119
	v_lshlrev_b32_e32 v38, 16, v115
	v_add_f32_e32 v58, v58, v59
	v_lshlrev_b32_e32 v59, 16, v42
	v_add_f32_e32 v34, v34, v38
	v_lshlrev_b32_e32 v38, 16, v43
	v_lshlrev_b32_e32 v42, 16, v39
	v_add_f32_e32 v38, v42, v38
	v_and_b32_e32 v43, 0xffff0000, v43
	v_and_b32_e32 v42, 0xffff0000, v115
	v_and_b32_e32 v47, 0xffff0000, v39
	v_and_b32_e32 v46, 0xffff0000, v119
	v_pk_add_f32 v[42:43], v[42:43], v[46:47]
	v_lshlrev_b32_e32 v35, 16, v116
	v_lshlrev_b32_e32 v47, 16, v120
	v_add_f32_e32 v64, v47, v35
	v_lshlrev_b32_e32 v35, 16, v44
	v_and_b32_e32 v47, 0xffff0000, v44
	v_lshlrev_b32_e32 v44, 16, v40
	v_lshlrev_b32_e32 v39, 16, v117
	v_add_f32_e32 v44, v44, v35
	v_lshlrev_b32_e32 v35, 16, v121
	v_and_b32_e32 v46, 0xffff0000, v116
	v_and_b32_e32 v48, 0xffff0000, v117
	v_and_b32_e32 v49, 0xffff0000, v45
	v_lshlrev_b32_e32 v45, 16, v45
	v_and_b32_e32 v67, 0xffff0000, v40
	v_and_b32_e32 v66, 0xffff0000, v120
	v_add_f32_e32 v36, v35, v39
	v_lshlrev_b32_e32 v35, 16, v41
	v_pk_add_f32 v[46:47], v[46:47], v[66:67]
	v_add_f32_e32 v40, v35, v45
	v_and_b32_e32 v67, 0xffff0000, v41
	v_and_b32_e32 v66, 0xffff0000, v121
	v_mov_b32_e32 v35, v42
	v_mov_b32_e32 v39, v43
	v_pk_add_f32 v[48:49], v[48:49], v[66:67]
	v_pk_add_f32 v[34:35], v[34:35], v[38:39]
	v_mov_b32_e32 v65, v46
	v_mov_b32_e32 v45, v47
	v_add_f32_e32 v60, v60, v59
	v_mov_b32_e32 v59, v62
	v_mov_b32_e32 v61, v63
	s_waitcnt vmcnt(1)
	v_pk_fma_f32 v[8:9], v[152:153], v[34:35], v[8:9]
	v_pk_add_f32 v[34:35], v[64:65], v[44:45]
	v_mov_b32_e32 v37, v48
	v_mov_b32_e32 v41, v49
	v_pk_add_f32 v[58:59], v[58:59], v[60:61]
	s_waitcnt vmcnt(0)
	v_pk_fma_f32 v[2:3], v[154:155], v[34:35], v[2:3]
	v_pk_add_f32 v[34:35], v[36:37], v[40:41]
	v_pk_fma_f32 v[6:7], v[150:151], v[58:59], v[6:7]
	v_pk_fma_f32 v[4:5], v[156:157], v[34:35], v[4:5]

.LBB0_426:
	s_andn2_b64 vcc, exec, s[12:13]
	s_cbranch_vccnz .LBB0_428
	v_or_b32_e32 v0, s14, v170
	v_lshlrev_b64 v[2:3], 10, v[0:1]
	v_lshl_or_b32 v2, s9, 7, v2
	s_lshl_b32 s12, s16, 4
	v_or_b32_e32 v2, s12, v2
	v_lshlrev_b64 v[2:3], 1, v[2:3]
	v_lshl_add_u64 v[4:5], s[30:31], 0, v[2:3]
	global_load_dwordx4 v[84:87], v[4:5], off offset:16
	global_load_dwordx4 v[92:95], v[4:5], off
	v_lshl_add_u64 v[10:11], s[42:43], 0, v[2:3]
	global_load_dwordx4 v[88:91], v[10:11], off offset:16
	global_load_dwordx4 v[96:99], v[10:11], off
	global_load_dwordx4 v[6:9], v[4:5], off offset:144
	global_load_dwordx4 v[80:83], v[4:5], off offset:128
	global_load_dwordx4 v[130:133], v[10:11], off offset:144
	global_load_dwordx4 v[134:137], v[10:11], off offset:128
	v_mov_b64_e32 v[2:3], s[74:75]
	v_mad_u64_u32 v[2:3], s[0:1], v0, s85, v[2:3]
	s_lshl_b32 s46, s9, 8
	v_lshl_add_u64 v[2:3], v[2:3], 0, s[46:47]
	s_lshl_b32 s46, s16, 5
	v_lshl_add_u64 v[100:101], v[2:3], 0, s[46:47]
	s_nop 0
	s_nop 0
	s_nop 0
	s_nop 0
	s_nop 0
	s_nop 0
	s_nop 0
	s_nop 0
	s_nop 0
	s_nop 0
	v_add_u32_e32 v0, s46, v179
	s_or_b32 s0, s12, 1
	s_mul_i32 s1, s0, 0x90
	s_add_i32 s12, s1, 0x90
	s_mulk_i32 s0, 0x88
	v_lshl_add_u64 v[14:15], v[100:101], 0, s[40:41]
	s_waitcnt vmcnt(8)
	v_mov_b32_e32 v208, 0
	v_mov_b32_e32 v207, 0
	s_waitcnt vmcnt(6)
	ds_write2_b64 v0, v[92:93], v[94:95] offset1:1
	v_add_co_u32_e32 v92, vcc, s33, v100
	v_add_u32_e32 v0, 0x4200, v0
	s_nop 0
	v_addc_co_u32_e32 v93, vcc, 0, v101, vcc
	global_load_dwordx4 v[92:95], v[92:93], off
	global_load_dwordx4 v[140:143], v[14:15], off offset:16
	global_load_dwordx4 v[144:147], v[14:15], off offset:128
	global_load_dwordx4 v[100:103], v[14:15], off offset:144
	s_waitcnt vmcnt(8)
	ds_write2_b64 v0, v[96:97], v[98:99] offset1:1
	v_add_u32_e32 v0, s88, v189
	ds_write_b16 v0, v96 offset:33792
	v_add_u32_e32 v0, s1, v189
	ds_write_b16_d16_hi v0, v96 offset:33792
	v_add_u32_e32 v0, s12, v189
	s_add_i32 s12, s1, 0x120
	ds_write_b16 v0, v97 offset:33792
	v_add_u32_e32 v0, s12, v189
	s_add_i32 s12, s1, 0x1b0
	ds_write_b16_d16_hi v0, v97 offset:33792
	v_add_u32_e32 v0, s12, v189
	s_add_i32 s12, s1, 0x240
	ds_write_b16 v0, v98 offset:33792
	v_add_u32_e32 v0, s12, v189
	s_add_i32 s12, s1, 0x2d0
	ds_write_b16_d16_hi v0, v98 offset:33792
	v_add_u32_e32 v0, s12, v189
	s_addk_i32 s1, 0x360
	ds_write_b16 v0, v99 offset:33792
	v_add_u32_e32 v0, s1, v189
	ds_write_b16_d16_hi v0, v99 offset:33792
	v_add_u32_e32 v0, s17, v189
	s_add_i32 s1, s0, 0x88
	s_waitcnt vmcnt(3)
	ds_write_b16 v0, v92 offset:52224
	v_add_u32_e32 v0, s0, v189
	ds_write_b16_d16_hi v0, v92 offset:52224
	v_add_u32_e32 v0, s1, v189
	s_add_i32 s1, s0, 0x110
	ds_write_b16 v0, v93 offset:52224
	v_add_u32_e32 v0, s1, v189
	s_add_i32 s1, s0, 0x198
	ds_write_b16_d16_hi v0, v93 offset:52224
	v_add_u32_e32 v0, s1, v189
	s_add_i32 s1, s0, 0x220
	ds_write_b16 v0, v94 offset:52224
	v_add_u32_e32 v0, s1, v189
	s_add_i32 s1, s0, 0x2a8
	ds_write_b16_d16_hi v0, v94 offset:52224
	v_add_u32_e32 v0, s1, v189
	s_addk_i32 s0, 0x330
	ds_write_b16 v0, v95 offset:52224
	v_add_u32_e32 v0, s0, v189
	ds_write_b16_d16_hi v0, v95 offset:52224
	s_nop 0
	s_nop 0
	s_nop 0
	s_lshl_b32 s0, s16, 1
	s_or_b32 s1, s0, 1
	v_lshl_add_u32 v0, s1, 4, v179
	s_lshl_b32 s12, s1, 3
	ds_write2_b64 v0, v[84:85], v[86:87] offset1:1
	v_add_u32_e32 v0, 0x4200, v0
	s_mul_i32 s13, s1, 0x480
	s_or_b32 s12, s12, 1
	ds_write2_b64 v0, v[88:89], v[90:91] offset1:1
	v_add_u32_e32 v0, s13, v189
	s_mul_i32 s13, s12, 0x90
	ds_write_b16 v0, v88 offset:33792
	v_add_u32_e32 v0, s13, v189
	s_add_i32 s14, s13, 0x90
	ds_write_b16_d16_hi v0, v88 offset:33792
	v_add_u32_e32 v0, s14, v189
	s_add_i32 s14, s13, 0x120
	ds_write_b16 v0, v89 offset:33792
	v_add_u32_e32 v0, s14, v189
	s_add_i32 s14, s13, 0x1b0
	ds_write_b16_d16_hi v0, v89 offset:33792
	v_add_u32_e32 v0, s14, v189
	s_add_i32 s14, s13, 0x240
	ds_write_b16 v0, v90 offset:33792
	v_add_u32_e32 v0, s14, v189
	s_add_i32 s14, s13, 0x2d0
	ds_write_b16_d16_hi v0, v90 offset:33792
	v_add_u32_e32 v0, s14, v189
	s_addk_i32 s13, 0x360
	ds_write_b16 v0, v91 offset:33792
	v_add_u32_e32 v0, s13, v189
	s_mulk_i32 s1, 0x440
	ds_write_b16_d16_hi v0, v91 offset:33792
	v_add_u32_e32 v0, s1, v189
	s_mul_i32 s1, s12, 0x88
	s_add_i32 s12, s1, 0x88
	s_waitcnt vmcnt(2)
	ds_write_b16 v0, v140 offset:52224
	v_add_u32_e32 v0, s1, v189
	ds_write_b16_d16_hi v0, v140 offset:52224
	v_add_u32_e32 v0, s12, v189
	s_add_i32 s12, s1, 0x110
	ds_write_b16 v0, v141 offset:52224
	v_add_u32_e32 v0, s12, v189
	s_add_i32 s12, s1, 0x198
	ds_write_b16_d16_hi v0, v141 offset:52224
	v_add_u32_e32 v0, s12, v189
	s_add_i32 s12, s1, 0x220
	ds_write_b16 v0, v142 offset:52224
	v_add_u32_e32 v0, s12, v189
	s_add_i32 s12, s1, 0x2a8
	ds_write_b16_d16_hi v0, v142 offset:52224
	v_add_u32_e32 v0, s12, v189
	s_addk_i32 s1, 0x330
	ds_write_b16 v0, v143 offset:52224
	v_add_u32_e32 v0, s1, v189
	s_or_b32 s1, s0, 8
	ds_write_b16_d16_hi v0, v143 offset:52224
	v_lshl_add_u32 v0, s1, 4, v179
	s_lshl_b32 s12, s1, 3
	ds_write2_b64 v0, v[80:81], v[82:83] offset1:1
	v_add_u32_e32 v0, 0x4200, v0
	s_mul_i32 s13, s1, 0x480
	s_or_b32 s12, s12, 1
	ds_write2_b64 v0, v[134:135], v[136:137] offset1:1
	v_add_u32_e32 v0, s13, v189
	s_mul_i32 s13, s12, 0x90
	ds_write_b16 v0, v134 offset:33792
	v_add_u32_e32 v0, s13, v189
	s_add_i32 s14, s13, 0x90
	ds_write_b16_d16_hi v0, v134 offset:33792
	v_add_u32_e32 v0, s14, v189
	s_add_i32 s14, s13, 0x120
	ds_write_b16 v0, v135 offset:33792
	v_add_u32_e32 v0, s14, v189
	s_add_i32 s14, s13, 0x1b0
	ds_write_b16_d16_hi v0, v135 offset:33792
	v_add_u32_e32 v0, s14, v189
	s_add_i32 s14, s13, 0x240
	ds_write_b16 v0, v136 offset:33792
	v_add_u32_e32 v0, s14, v189
	s_add_i32 s14, s13, 0x2d0
	ds_write_b16_d16_hi v0, v136 offset:33792
	v_add_u32_e32 v0, s14, v189
	s_addk_i32 s13, 0x360
	ds_write_b16 v0, v137 offset:33792
	v_add_u32_e32 v0, s13, v189
	s_mulk_i32 s1, 0x440
	ds_write_b16_d16_hi v0, v137 offset:33792
	v_add_u32_e32 v0, s1, v189
	s_mul_i32 s1, s12, 0x88
	s_waitcnt vmcnt(1)
	ds_write_b16 v0, v144 offset:52224
	v_add_u32_e32 v0, s1, v189
	s_add_i32 s12, s1, 0x88
	ds_write_b16_d16_hi v0, v144 offset:52224
	v_add_u32_e32 v0, s12, v189
	s_add_i32 s12, s1, 0x110
	ds_write_b16 v0, v145 offset:52224
	v_add_u32_e32 v0, s12, v189
	s_add_i32 s12, s1, 0x198
	ds_write_b16_d16_hi v0, v145 offset:52224
	v_add_u32_e32 v0, s12, v189
	s_add_i32 s12, s1, 0x220
	ds_write_b16 v0, v146 offset:52224
	v_add_u32_e32 v0, s12, v189
	s_add_i32 s12, s1, 0x2a8
	ds_write_b16_d16_hi v0, v146 offset:52224
	v_add_u32_e32 v0, s12, v189
	s_addk_i32 s1, 0x330
	ds_write_b16 v0, v147 offset:52224
	v_add_u32_e32 v0, s1, v189
	s_or_b32 s0, s0, 9
	ds_write_b16_d16_hi v0, v147 offset:52224
	v_lshl_add_u32 v0, s0, 4, v179
	s_lshl_b32 s1, s0, 3
	ds_write2_b64 v0, v[6:7], v[8:9] offset1:1
	v_add_u32_e32 v0, 0x4200, v0
	s_mul_i32 s12, s0, 0x480
	s_or_b32 s1, s1, 1
	ds_write2_b64 v0, v[130:131], v[132:133] offset1:1
	v_add_u32_e32 v0, s12, v189
	s_mul_i32 s12, s1, 0x90
	ds_write_b16 v0, v130 offset:33792
	v_add_u32_e32 v0, s12, v189
	s_add_i32 s13, s12, 0x90
	ds_write_b16_d16_hi v0, v130 offset:33792
	v_add_u32_e32 v0, s13, v189
	s_add_i32 s13, s12, 0x120
	ds_write_b16 v0, v131 offset:33792
	v_add_u32_e32 v0, s13, v189
	s_add_i32 s13, s12, 0x1b0
	ds_write_b16_d16_hi v0, v131 offset:33792
	v_add_u32_e32 v0, s13, v189
	s_add_i32 s13, s12, 0x240
	ds_write_b16 v0, v132 offset:33792
	v_add_u32_e32 v0, s13, v189
	s_add_i32 s13, s12, 0x2d0
	ds_write_b16_d16_hi v0, v132 offset:33792
	v_add_u32_e32 v0, s13, v189
	s_addk_i32 s12, 0x360
	ds_write_b16 v0, v133 offset:33792
	v_add_u32_e32 v0, s12, v189
	s_mulk_i32 s0, 0x440
	ds_write_b16_d16_hi v0, v133 offset:33792
	v_add_u32_e32 v0, s0, v189
	s_mul_i32 s0, s1, 0x88
	s_waitcnt vmcnt(0)
	ds_write_b16 v0, v100 offset:52224
	v_add_u32_e32 v0, s0, v189
	s_add_i32 s1, s0, 0x88
	ds_write_b16_d16_hi v0, v100 offset:52224
	v_add_u32_e32 v0, s1, v189
	s_add_i32 s1, s0, 0x110
	ds_write_b16 v0, v101 offset:52224
	v_add_u32_e32 v0, s1, v189
	s_add_i32 s1, s0, 0x198
	ds_write_b16_d16_hi v0, v101 offset:52224
	v_add_u32_e32 v0, s1, v189
	s_add_i32 s1, s0, 0x220
	ds_write_b16 v0, v102 offset:52224
	v_add_u32_e32 v0, s1, v189
	s_add_i32 s1, s0, 0x2a8
	ds_write_b16_d16_hi v0, v102 offset:52224
	v_add_u32_e32 v0, s1, v189
	s_addk_i32 s0, 0x330
	ds_write_b16 v0, v103 offset:52224
	v_add_u32_e32 v0, s0, v189
	ds_write_b16_d16_hi v0, v103 offset:52224
	v_mov_b32_e32 v3, v131
	v_mov_b32_e32 v11, v135
	v_mov_b32_e32 v12, v136
	v_mov_b32_e32 v13, v137
	v_mov_b32_e32 v98, v146
	v_mov_b32_e32 v99, v147

.LBB0_430:
	s_not_b32 s8, s0
	s_add_i32 s12, s68, s8
	s_and_b64 s[8:9], s[10:11], exec
	s_cselect_b32 s8, s0, s12
	s_waitcnt lgkmcnt(0)
	s_barrier
	s_lshl_b32 s8, s8, 6
	s_add_i32 s8, s8, s69
	s_and_b64 vcc, exec, s[54:55]
	s_cbranch_vccz .LBB0_445
	v_or_b32_e32 v2, s8, v170
	v_ashrrev_i32_e32 v3, 31, v2
	v_lshlrev_b64 v[4:5], 11, v[2:3]
	s_lshl_b64 s[12:13], s[38:39], 1
	v_or_b32_e32 v5, s13, v5
	v_or_b32_e32 v4, s12, v4
	v_lshl_add_u64 v[12:13], s[30:31], 0, v[4:5]
	global_load_dwordx4 v[104:107], v[12:13], off offset:16
	global_load_dwordx4 v[8:11], v[12:13], off
	v_lshl_add_u64 v[84:85], s[42:43], 0, v[4:5]
	global_load_dwordx4 v[100:103], v[84:85], off offset:16
	global_load_dwordx4 v[80:83], v[84:85], off
	global_load_dwordx4 v[88:91], v[12:13], off offset:144
	global_load_dwordx4 v[96:99], v[12:13], off offset:128
	global_load_dwordx4 v[130:133], v[84:85], off offset:144
	global_load_dwordx4 v[92:95], v[84:85], off offset:128
	v_mov_b64_e32 v[4:5], s[74:75]
	v_mad_i64_i32 v[2:3], s[12:13], v2, s85, v[4:5]
	s_lshl_b32 s46, s83, 1
	v_lshl_add_u64 v[2:3], v[2:3], 0, s[46:47]
	s_lshl_b32 s46, s29, 1
	v_lshl_add_u64 v[86:87], v[2:3], 0, s[46:47]
	s_nop 0
	s_nop 0
	s_nop 0
	s_nop 0
	s_nop 0
	s_nop 0
	s_nop 0
	s_nop 0
	v_or_b32_e32 v12, s8, v206
	v_ashrrev_i32_e32 v13, 31, v12
	v_lshlrev_b64 v[12:13], 5, v[12:13]
	v_lshl_add_u64 v[84:85], s[56:57], 0, v[12:13]
	global_load_dword v0, v[84:85], off
	v_lshl_add_u64 v[12:13], s[2:3], 0, v[12:13]
	global_load_dword v108, v[12:13], off
	s_nop 0
	s_nop 0
	v_add_u32_e32 v12, s1, v209
	v_lshl_add_u64 v[6:7], v[86:87], 0, s[40:41]
	v_add_u32_e32 v109, s18, v209
	s_waitcnt vmcnt(10)
	s_waitcnt vmcnt(8)
	ds_write2_b64 v12, v[8:9], v[10:11] offset1:1
	v_add_u32_e32 v8, 0x4200, v12
	s_waitcnt vmcnt(6)
	ds_write2_b64 v8, v[80:81], v[82:83] offset1:1
	v_add_u32_e32 v8, s88, v210
	ds_write_b16 v8, v80 offset:33792
	v_add_u32_e32 v8, s27, v210
	ds_write_b16_d16_hi v8, v80 offset:33792
	ds_write_b16 v8, v81 offset:33936
	ds_write_b16_d16_hi v8, v81 offset:34080
	ds_write_b16 v8, v82 offset:34224
	ds_write_b16_d16_hi v8, v82 offset:34368
	ds_write_b16 v8, v83 offset:34512
	ds_write_b16_d16_hi v8, v83 offset:34656
	v_add_co_u32_e32 v8, vcc, s33, v86
	s_nop 1
	v_addc_co_u32_e32 v9, vcc, 0, v87, vcc
	global_load_dwordx4 v[84:87], v[8:9], off
	global_load_dwordx4 v[80:83], v[6:7], off offset:16
	global_load_dwordx4 v[10:13], v[6:7], off offset:128
	global_load_dwordx4 v[134:137], v[6:7], off offset:144
	s_nop 0
	s_nop 0
	s_nop 0
	s_nop 0
	ds_write2_b64 v109, v[104:105], v[106:107] offset1:1
	v_add_u32_e32 v104, 0x4200, v109
	ds_write2_b64 v104, v[100:101], v[102:103] offset1:1
	v_add_u32_e32 v104, s19, v210
	v_add_u32_e32 v105, s64, v210
	ds_write_b16 v104, v100 offset:33792
	ds_write_b16_d16_hi v105, v100 offset:33792
	ds_write_b16 v105, v101 offset:33936
	ds_write_b16_d16_hi v105, v101 offset:34080
	ds_write_b16 v105, v102 offset:34224
	ds_write_b16_d16_hi v105, v102 offset:34368
	ds_write_b16 v105, v103 offset:34512
	ds_write_b16_d16_hi v105, v103 offset:34656
	v_add_u32_e32 v100, s90, v209
	s_waitcnt vmcnt(8)
	ds_write2_b64 v100, v[96:97], v[98:99] offset1:1
	v_add_u32_e32 v96, 0x4200, v100
	s_waitcnt vmcnt(6)
	ds_write2_b64 v96, v[92:93], v[94:95] offset1:1
	ds_write_b16 v104, v92 offset:41856
	v_add_u32_e32 v96, s91, v210
	ds_write_b16_d16_hi v96, v92 offset:33792
	ds_write_b16 v96, v93 offset:33936
	ds_write_b16_d16_hi v96, v93 offset:34080
	ds_write_b16 v96, v94 offset:34224
	ds_write_b16_d16_hi v96, v94 offset:34368
	ds_write_b16 v96, v95 offset:34512
	ds_write_b16_d16_hi v96, v95 offset:34656
	v_add_u32_e32 v92, s67, v209
	ds_write2_b64 v92, v[88:89], v[90:91] offset1:1
	v_add_u32_e32 v88, 0x4200, v92
	ds_write2_b64 v88, v[130:131], v[132:133] offset1:1
	ds_write_b16 v104, v130 offset:43008
	v_add_u32_e32 v88, s24, v210
	ds_write_b16_d16_hi v88, v130 offset:33792
	ds_write_b16 v88, v131 offset:33936
	ds_write_b16_d16_hi v88, v131 offset:34080
	ds_write_b16 v88, v132 offset:34224
	ds_write_b16_d16_hi v88, v132 offset:34368
	ds_write_b16 v88, v133 offset:34512
	ds_write_b16_d16_hi v88, v133 offset:34656
	s_waitcnt vmcnt(4)
	v_add_f32_dpp v130, v108, v108 row_shr:1 row_mask:0xf bank_mask:0xf bound_ctrl:1
	v_mov_b32_e32 v3, v1
	v_mov_b32_e32 v4, 0xff61b1e6
	v_add_f32_dpp v130, v130, v130 row_shr:2 row_mask:0xf bank_mask:0xf bound_ctrl:1
	s_nop 1
	v_add_f32_dpp v130, v130, v130 row_shr:4 row_mask:0xf bank_mask:0xf bound_ctrl:1
	s_nop 1
	v_add_f32_dpp v130, v130, v130 row_shr:8 row_mask:0xf bank_mask:0xf bound_ctrl:1
	s_nop 1
	v_mov_b32_dpp v3, v130 row_bcast:15 row_mask:0xa bank_mask:0xf
	v_add_f32_e32 v130, v130, v3
	v_mov_b32_e32 v3, v1
	s_nop 1
	v_mov_b32_dpp v3, v130 row_bcast:31 row_mask:0xc bank_mask:0xf
	v_add_f32_e32 v130, v130, v3
	v_sub_f32_e32 v0, v0, v130
	v_mov_b32_e32 v3, 0xff61b1e6
	s_nop 1
	v_mov_b32_dpp v3, v0 row_shr:1 row_mask:0xf bank_mask:0xf
	v_max_f32_e32 v3, v0, v3
	s_nop 1
	v_mov_b32_dpp v4, v3 row_shr:2 row_mask:0xf bank_mask:0xf
	v_max_f32_e32 v3, v3, v4
	v_mov_b32_e32 v4, 0xff61b1e6
	s_nop 1
	v_mov_b32_dpp v4, v3 row_shr:4 row_mask:0xf bank_mask:0xf
	v_max_f32_e32 v3, v3, v4
	v_mov_b32_e32 v4, 0xff61b1e6
	s_nop 1
	v_mov_b32_dpp v4, v3 row_shr:8 row_mask:0xf bank_mask:0xf
	v_max_f32_e32 v3, v3, v4
	v_mov_b32_e32 v4, 0xff61b1e6
	s_nop 1
	v_mov_b32_dpp v4, v3 row_bcast:15 row_mask:0xa bank_mask:0xf
	v_max_f32_e32 v3, v3, v4
	v_mov_b32_e32 v4, 0xff61b1e6
	s_nop 1
	v_mov_b32_dpp v4, v3 row_bcast:31 row_mask:0xc bank_mask:0xf
	v_max3_f32 v3, v217, v3, v4
	s_nop 0
	v_readlane_b32 s9, v3, 63
	s_nop 1
	v_subrev_f32_e32 v4, s9, v0
	v_mul_f32_e32 v4, 0x3fb8aa3b, v4
	v_exp_f32_e32 v4, v4
	ds_write2st64_b32 v211, v0, v3 offset1:1
	ds_write2st64_b32 v211, v130, v4 offset0:2 offset1:3
	v_add_u32_e32 v0, s17, v210
	s_waitcnt vmcnt(3)
	ds_write_b16 v0, v84 offset:52224
	v_add_u32_e32 v0, s78, v210
	ds_write_b16_d16_hi v0, v84 offset:52224
	ds_write_b16 v0, v85 offset:52360
	ds_write_b16_d16_hi v0, v85 offset:52496
	ds_write_b16 v0, v86 offset:52632
	ds_write_b16_d16_hi v0, v86 offset:52768
	ds_write_b16 v0, v87 offset:52904
	ds_write_b16_d16_hi v0, v87 offset:53040
	v_add_u32_e32 v0, s79, v210
	v_add_u32_e32 v2, s65, v210
	s_waitcnt vmcnt(2)
	ds_write_b16 v0, v80 offset:52224
	ds_write_b16_d16_hi v2, v80 offset:52224
	ds_write_b16 v2, v81 offset:52360
	ds_write_b16_d16_hi v2, v81 offset:52496
	ds_write_b16 v2, v82 offset:52632
	ds_write_b16_d16_hi v2, v82 offset:52768
	ds_write_b16 v2, v83 offset:52904
	ds_write_b16_d16_hi v2, v83 offset:53040
	s_waitcnt vmcnt(1)
	ds_write_b16 v0, v10 offset:59840
	v_add_u32_e32 v2, s66, v210
	ds_write_b16_d16_hi v2, v10 offset:52224
	ds_write_b16 v2, v11 offset:52360
	ds_write_b16_d16_hi v2, v11 offset:52496
	ds_write_b16 v2, v12 offset:52632
	ds_write_b16_d16_hi v2, v12 offset:52768
	ds_write_b16 v2, v13 offset:52904
	ds_write_b16_d16_hi v2, v13 offset:53040
	s_waitcnt vmcnt(0)
	ds_write_b16 v0, v134 offset:60928
	v_add_u32_e32 v0, s25, v210
	ds_write_b16_d16_hi v0, v134 offset:52224
	ds_write_b16 v0, v135 offset:52360
	ds_write_b16_d16_hi v0, v135 offset:52496
	ds_write_b16 v0, v136 offset:52632
	ds_write_b16_d16_hi v0, v136 offset:52768
	ds_write_b16 v0, v137 offset:52904
	ds_write_b16_d16_hi v0, v137 offset:53040
	s_waitcnt lgkmcnt(0)
	s_barrier
	s_mov_b64 s[12:13], -1
	s_cbranch_execz .LBB0_446
	s_mov_b32 s46, s28
	s_and_b64 vcc, exec, s[12:13]
	s_cbranch_vccz .LBB0_455

.LBB0_446:
	s_sub_i32 s14, s26, s0
	s_add_i32 s9, s0, 1
	s_and_b64 s[12:13], s[10:11], exec
	s_cselect_b32 s12, s9, s14
	s_lshl_b32 s20, s12, 6
	s_add_i32 s20, s20, s69
	s_cmp_lt_u32 s9, s68
	s_cselect_b64 s[12:13], -1, 0
	v_cndmask_b32_e64 v0, 0, 1, s[12:13]
	s_mov_b64 s[14:15], -1
	s_andn2_b64 vcc, exec, s[36:37]
	v_cmp_ne_u32_e64 s[12:13], 1, v0
	s_cbranch_vccnz .LBB0_450
	s_and_b64 vcc, exec, s[12:13]
	s_cbranch_vccnz .LBB0_449
	s_bitcmp1_b32 s9, 0
	v_or_b32_e32 v2, s20, v170
	s_cselect_b32 s14, 0x11000, 0
	v_ashrrev_i32_e32 v3, 31, v2
	s_add_i32 s21, s14, 0
	v_lshlrev_b64 v[4:5], 11, v[2:3]
	s_lshl_b64 s[14:15], s[38:39], 1
	v_or_b32_e32 v5, s15, v5
	v_or_b32_e32 v4, s14, v4
	v_lshl_add_u64 v[10:11], s[30:31], 0, v[4:5]
	global_load_dwordx4 v[96:99], v[10:11], off offset:16
	global_load_dwordx4 v[84:87], v[10:11], off
	v_lshl_add_u64 v[12:13], s[42:43], 0, v[4:5]
	global_load_dwordx4 v[88:91], v[12:13], off offset:16
	global_load_dwordx4 v[102:105], v[12:13], off
	global_load_dwordx4 v[6:9], v[10:11], off offset:144
	global_load_dwordx4 v[80:83], v[10:11], off offset:128
	global_load_dwordx4 v[130:133], v[12:13], off offset:144
	global_load_dwordx4 v[134:137], v[12:13], off offset:128
	v_mov_b64_e32 v[4:5], s[74:75]
	v_mad_i64_i32 v[2:3], s[14:15], v2, s85, v[4:5]
	s_lshl_b32 s46, s83, 1
	v_lshl_add_u64 v[2:3], v[2:3], 0, s[46:47]
	s_lshl_b32 s46, s29, 1
	v_lshl_add_u64 v[94:95], v[2:3], 0, s[46:47]
	s_nop 0
	s_nop 0
	s_nop 0
	s_nop 0
	s_nop 0
	s_nop 0
	s_nop 0
	s_nop 0
	s_nop 0
	v_add_u32_e32 v100, s21, v175
	v_add_u32_e32 v0, s1, v100
	v_lshl_add_u64 v[92:93], v[94:95], 0, s[40:41]
	s_waitcnt vmcnt(8)
	s_waitcnt vmcnt(6)
	ds_write2_b64 v0, v[84:85], v[86:87] offset1:1
	v_add_u32_e32 v0, 0x4200, v0
	s_waitcnt vmcnt(4)
	ds_write2_b64 v0, v[102:103], v[104:105] offset1:1
	v_add_u32_e32 v0, s21, v188
	v_add_u32_e32 v84, s88, v0
	ds_write_b16 v84, v102 offset:33792
	v_add_u32_e32 v84, s27, v0
	ds_write_b16_d16_hi v84, v102 offset:33792
	ds_write_b16 v84, v103 offset:33936
	ds_write_b16_d16_hi v84, v103 offset:34080
	ds_write_b16 v84, v104 offset:34224
	ds_write_b16_d16_hi v84, v104 offset:34368
	ds_write_b16 v84, v105 offset:34512
	ds_write_b16_d16_hi v84, v105 offset:34656
	v_add_co_u32_e32 v84, vcc, s33, v94
	v_add_u32_e32 v101, s17, v0
	s_nop 0
	v_addc_co_u32_e32 v85, vcc, 0, v95, vcc
	global_load_dwordx4 v[84:87], v[84:85], off
	global_load_dwordx4 v[102:105], v[92:93], off offset:16
	global_load_dwordx4 v[140:143], v[92:93], off offset:128
	global_load_dwordx4 v[144:147], v[92:93], off offset:144
	v_add_u32_e32 v94, s78, v0
	s_waitcnt vmcnt(3)
	ds_write_b16 v101, v84 offset:52224
	ds_write_b16_d16_hi v94, v84 offset:52224
	ds_write_b16 v94, v85 offset:52360
	ds_write_b16_d16_hi v94, v85 offset:52496
	ds_write_b16 v94, v86 offset:52632
	ds_write_b16_d16_hi v94, v86 offset:52768
	ds_write_b16 v94, v87 offset:52904
	ds_write_b16_d16_hi v94, v87 offset:53040
	s_nop 0
	s_nop 0
	s_nop 0
	s_nop 0
	v_add_u32_e32 v101, s18, v100
	ds_write2_b64 v101, v[96:97], v[98:99] offset1:1
	v_add_u32_e32 v96, 0x4200, v101
	ds_write2_b64 v96, v[88:89], v[90:91] offset1:1
	v_add_u32_e32 v96, s19, v0
	v_add_u32_e32 v97, s64, v0
	ds_write_b16 v96, v88 offset:33792
	ds_write_b16_d16_hi v97, v88 offset:33792
	ds_write_b16 v97, v89 offset:33936
	ds_write_b16_d16_hi v97, v89 offset:34080
	ds_write_b16 v97, v90 offset:34224
	ds_write_b16_d16_hi v97, v90 offset:34368
	ds_write_b16 v97, v91 offset:34512
	ds_write_b16_d16_hi v97, v91 offset:34656
	v_add_u32_e32 v88, s79, v0
	v_add_u32_e32 v89, s65, v0
	s_waitcnt vmcnt(2)
	ds_write_b16 v88, v102 offset:52224
	ds_write_b16_d16_hi v89, v102 offset:52224
	ds_write_b16 v89, v103 offset:52360
	ds_write_b16_d16_hi v89, v103 offset:52496
	ds_write_b16 v89, v104 offset:52632
	ds_write_b16_d16_hi v89, v104 offset:52768
	ds_write_b16 v89, v105 offset:52904
	ds_write_b16_d16_hi v89, v105 offset:53040
	v_add_u32_e32 v89, s90, v100
	ds_write2_b64 v89, v[80:81], v[82:83] offset1:1
	v_add_u32_e32 v80, 0x4200, v89
	ds_write2_b64 v80, v[134:135], v[136:137] offset1:1
	ds_write_b16 v96, v134 offset:41856
	v_add_u32_e32 v80, s91, v0
	ds_write_b16_d16_hi v80, v134 offset:33792
	ds_write_b16 v80, v135 offset:33936
	ds_write_b16_d16_hi v80, v135 offset:34080
	ds_write_b16 v80, v136 offset:34224
	ds_write_b16_d16_hi v80, v136 offset:34368
	ds_write_b16 v80, v137 offset:34512
	ds_write_b16_d16_hi v80, v137 offset:34656
	s_waitcnt vmcnt(1)
	ds_write_b16 v88, v140 offset:59840
	v_add_u32_e32 v10, s66, v0
	ds_write_b16_d16_hi v10, v140 offset:52224
	ds_write_b16 v10, v141 offset:52360
	ds_write_b16_d16_hi v10, v141 offset:52496
	ds_write_b16 v10, v142 offset:52632
	ds_write_b16_d16_hi v10, v142 offset:52768
	ds_write_b16 v10, v143 offset:52904
	ds_write_b16_d16_hi v10, v143 offset:53040
	v_add_u32_e32 v10, s67, v100
	ds_write2_b64 v10, v[6:7], v[8:9] offset1:1
	v_add_u32_e32 v6, 0x4200, v10
	ds_write2_b64 v6, v[130:131], v[132:133] offset1:1
	ds_write_b16 v96, v130 offset:43008
	v_add_u32_e32 v6, s24, v0
	v_add_u32_e32 v0, s25, v0
	ds_write_b16_d16_hi v6, v130 offset:33792
	ds_write_b16 v6, v131 offset:33936
	ds_write_b16_d16_hi v6, v131 offset:34080
	ds_write_b16 v6, v132 offset:34224
	ds_write_b16_d16_hi v6, v132 offset:34368
	ds_write_b16 v6, v133 offset:34512
	ds_write_b16_d16_hi v6, v133 offset:34656
	s_waitcnt vmcnt(0)
	ds_write_b16 v88, v144 offset:60928
	ds_write_b16_d16_hi v0, v144 offset:52224
	ds_write_b16 v0, v145 offset:52360
	ds_write_b16_d16_hi v0, v145 offset:52496
	ds_write_b16 v0, v146 offset:52632
	ds_write_b16_d16_hi v0, v146 offset:52768
	ds_write_b16 v0, v147 offset:52904
	ds_write_b16_d16_hi v0, v147 offset:53040
	v_mov_b32_e32 v3, v131
	v_mov_b32_e32 v11, v135
	v_mov_b32_e32 v12, v136
	v_mov_b32_e32 v13, v137

.LBB0_463:
	v_add_u32_e32 v56, s2, v70
	v_ashrrev_i32_e32 v57, 31, v56
	v_lshlrev_b64 v[2:3], 11, v[56:57]
	v_lshl_add_u64 v[2:3], s[62:63], 0, v[2:3]
	v_lshl_add_u64 v[2:3], v[2:3], 0, v[0:1]
	global_load_dwordx4 v[34:37], v[2:3], off
	v_add_co_u32_e32 v2, vcc, 0x1400000, v2
	v_mov_b64_e32 v[10:11], s[74:75]
	s_nop 0
	v_addc_co_u32_e32 v3, vcc, 0, v3, vcc
	global_load_dwordx4 v[38:41], v[2:3], off
	v_mad_i64_i32 v[2:3], s[2:3], v56, s85, v[10:11]
	v_lshl_add_u64 v[2:3], v[2:3], 0, v[0:1]
	v_add_co_u32_e32 v2, vcc, s4, v2
	v_add_u32_e32 v54, 32, v56
	s_nop 0
	v_addc_co_u32_e32 v3, vcc, 0, v3, vcc
	global_load_dwordx4 v[58:61], v[2:3], off offset:2048
	v_ashrrev_i32_e32 v55, 31, v54
	v_lshlrev_b64 v[2:3], 11, v[54:55]
	v_lshl_add_u64 v[2:3], s[62:63], 0, v[2:3]
	v_lshl_add_u64 v[2:3], v[2:3], 0, v[0:1]
	global_load_dwordx4 v[26:29], v[2:3], off
	v_add_co_u32_e32 v2, vcc, s5, v2
	v_add_u32_e32 v52, 64, v56
	s_nop 0
	v_addc_co_u32_e32 v3, vcc, 0, v3, vcc
	global_load_dwordx4 v[30:33], v[2:3], off
	v_mad_i64_i32 v[2:3], s[2:3], v54, s85, v[10:11]
	v_lshl_add_u64 v[2:3], v[2:3], 0, v[0:1]
	v_add_co_u32_e32 v2, vcc, s4, v2
	v_ashrrev_i32_e32 v53, 31, v52
	s_nop 0
	v_addc_co_u32_e32 v3, vcc, 0, v3, vcc
	global_load_dwordx4 v[42:45], v[2:3], off offset:2048
	v_lshlrev_b64 v[2:3], 11, v[52:53]
	v_lshl_add_u64 v[2:3], s[62:63], 0, v[2:3]
	v_lshl_add_u64 v[2:3], v[2:3], 0, v[0:1]
	global_load_dwordx4 v[14:17], v[2:3], off
	v_add_co_u32_e32 v2, vcc, s5, v2
	v_add_u32_e32 v50, 0x60, v56
	s_nop 0
	v_addc_co_u32_e32 v3, vcc, 0, v3, vcc
	global_load_dwordx4 v[18:21], v[2:3], off
	v_mad_i64_i32 v[2:3], s[2:3], v52, s85, v[10:11]
	v_lshl_add_u64 v[2:3], v[2:3], 0, v[0:1]
	v_add_co_u32_e32 v2, vcc, s4, v2
	v_ashrrev_i32_e32 v51, 31, v50
	s_nop 0
	v_addc_co_u32_e32 v3, vcc, 0, v3, vcc
	global_load_dwordx4 v[22:25], v[2:3], off offset:2048
	v_lshlrev_b64 v[2:3], 11, v[50:51]
	v_lshl_add_u64 v[2:3], s[62:63], 0, v[2:3]
	v_lshl_add_u64 v[6:7], v[2:3], 0, v[0:1]
	global_load_dwordx4 v[2:5], v[6:7], off
	v_add_co_u32_e32 v6, vcc, s5, v6
	v_mad_i64_i32 v[10:11], s[2:3], v50, s85, v[10:11]
	s_nop 0
	v_addc_co_u32_e32 v7, vcc, 0, v7, vcc
	global_load_dwordx4 v[6:9], v[6:7], off
	v_lshl_add_u64 v[10:11], v[10:11], 0, v[0:1]
	v_add_co_u32_e32 v10, vcc, s4, v10
	s_nop 0
	s_nop 0
	v_addc_co_u32_e32 v11, vcc, 0, v11, vcc
	global_load_dwordx4 v[10:13], v[10:11], off offset:2048
	s_movk_i32 s2, 0x80
	s_and_b64 vcc, exec, s[0:1]
	global_load_dwordx4 v[88:91], v[48:49], off offset:16
	global_load_dwordx4 v[76:79], v[48:49], off
	s_mov_b64 s[0:1], 0
	s_waitcnt vmcnt(14)
	s_waitcnt vmcnt(13)
	v_lshlrev_b32_e32 v72, 16, v36
	v_and_b32_e32 v73, 0xffff0000, v36
	v_lshlrev_b32_e32 v80, 16, v35
	v_and_b32_e32 v81, 0xffff0000, v35
	v_lshlrev_b32_e32 v84, 16, v34
	v_and_b32_e32 v85, 0xffff0000, v34
	s_waitcnt vmcnt(12)
	v_lshlrev_b32_e32 v36, 16, v40
	v_lshlrev_b32_e32 v34, 16, v38
	v_and_b32_e32 v35, 0xffff0000, v38
	v_lshlrev_b32_e32 v82, 16, v39
	v_and_b32_e32 v83, 0xffff0000, v39
	v_pk_add_f32 v[34:35], v[84:85], v[34:35]
	v_pk_add_f32 v[80:81], v[80:81], v[82:83]
	v_pk_mul_f32 v[38:39], v[34:35], v[34:35]
	v_pk_mul_f32 v[82:83], v[80:81], v[80:81]
	s_waitcnt vmcnt(11)
	v_lshlrev_b32_e32 v62, 16, v58
	v_and_b32_e32 v63, 0xffff0000, v58
	v_lshlrev_b32_e32 v66, 16, v60
	v_and_b32_e32 v67, 0xffff0000, v60
	v_lshlrev_b32_e32 v64, 16, v59
	v_and_b32_e32 v65, 0xffff0000, v59
	v_mul_f32_e32 v58, 0xbfb8aa3b, v62
	v_mul_f32_e32 v59, 0xbfb8aa3b, v63
	v_mul_f32_e32 v62, 0xbfb8aa3b, v66
	v_mul_f32_e32 v63, 0xbfb8aa3b, v67
	v_lshlrev_b32_e32 v66, 16, v37
	v_and_b32_e32 v67, 0xffff0000, v37
	v_and_b32_e32 v37, 0xffff0000, v40
	v_pk_add_f32 v[36:37], v[72:73], v[36:37]
	s_nop 0
	s_nop 0
	v_add_f32_e32 v38, v38, v39
	v_lshlrev_b32_e32 v68, 16, v61
	v_and_b32_e32 v69, 0xffff0000, v61
	v_add_f32_e32 v38, v82, v38
	v_mul_f32_e32 v60, 0xbfb8aa3b, v64
	v_mul_f32_e32 v61, 0xbfb8aa3b, v65
	v_mul_f32_e32 v64, 0xbfb8aa3b, v68
	v_mul_f32_e32 v65, 0xbfb8aa3b, v69
	v_lshlrev_b32_e32 v68, 16, v41
	v_and_b32_e32 v69, 0xffff0000, v41
	v_pk_mul_f32 v[40:41], v[36:37], v[36:37]
	v_add_f32_e32 v38, v83, v38
	v_pk_add_f32 v[66:67], v[66:67], v[68:69]
	v_add_f32_e32 v38, v40, v38
	v_pk_mul_f32 v[68:69], v[66:67], v[66:67]
	v_add_f32_e32 v38, v41, v38
	v_add_f32_e32 v38, v68, v38
	v_add_f32_e32 v38, v69, v38
	v_exp_f32_e32 v62, v62
	v_exp_f32_e32 v63, v63
	v_add_f32_dpp v38, v38, v38 quad_perm:[1,0,3,2] row_mask:0xf bank_mask:0xf bound_ctrl:1
	v_exp_f32_e32 v64, v64
	v_exp_f32_e32 v65, v65
	v_add_f32_dpp v38, v38, v38 quad_perm:[2,3,0,1] row_mask:0xf bank_mask:0xf bound_ctrl:1
	v_exp_f32_e32 v58, v58
	v_exp_f32_e32 v59, v59
	v_add_f32_dpp v38, v38, v38 row_half_mirror row_mask:0xf bank_mask:0xf bound_ctrl:1
	v_exp_f32_e32 v60, v60
	v_exp_f32_e32 v61, v61
	v_add_f32_dpp v38, v38, v38 row_mirror row_mask:0xf bank_mask:0xf bound_ctrl:1
	v_fmamk_f32 v38, v38, 0x3c000000, v233
	v_rsq_f32_e32 v38, v38
	v_add_f32_e32 v62, 1.0, v62
	v_add_f32_e32 v63, 1.0, v63
	v_add_f32_e32 v64, 1.0, v64
	v_add_f32_e32 v65, 1.0, v65
	v_add_f32_e32 v58, 1.0, v58
	v_add_f32_e32 v59, 1.0, v59
	v_add_f32_e32 v60, 1.0, v60
	v_add_f32_e32 v61, 1.0, v61
	v_rcp_f32_e32 v62, v62
	v_rcp_f32_e32 v63, v63
	v_rcp_f32_e32 v64, v64
	v_rcp_f32_e32 v65, v65
	v_rcp_f32_e32 v58, v58
	v_rcp_f32_e32 v59, v59
	v_rcp_f32_e32 v60, v60
	v_rcp_f32_e32 v61, v61
	v_pk_mul_f32 v[34:35], v[34:35], v[38:39] op_sel_hi:[1,0]
	v_pk_mul_f32 v[40:41], v[80:81], v[38:39] op_sel_hi:[1,0]
	v_pk_mul_f32 v[36:37], v[36:37], v[38:39] op_sel_hi:[1,0]
	v_pk_mul_f32 v[38:39], v[66:67], v[38:39] op_sel_hi:[1,0]
	s_waitcnt vmcnt(10)
	v_lshlrev_b32_e32 v68, 16, v26
	v_and_b32_e32 v69, 0xffff0000, v26
	s_waitcnt vmcnt(9)
	v_lshlrev_b32_e32 v26, 16, v30
	v_lshlrev_b32_e32 v66, 16, v31
	v_and_b32_e32 v67, 0xffff0000, v31
	s_waitcnt vmcnt(1)
	v_pk_mul_f32 v[36:37], v[88:89], v[36:37]
	v_pk_mul_f32 v[38:39], v[38:39], v[90:91]
	s_waitcnt vmcnt(0)
	v_pk_mul_f32 v[34:35], v[76:77], v[34:35]
	v_pk_mul_f32 v[40:41], v[78:79], v[40:41]
	v_pk_mul_f32 v[36:37], v[62:63], v[36:37]
	v_pk_mul_f32 v[38:39], v[64:65], v[38:39]
	v_pk_mul_f32 v[34:35], v[58:59], v[34:35]
	v_pk_mul_f32 v[40:41], v[60:61], v[40:41]
	v_cvt_pk_bf16_f32 v36, v36, v37
	v_cvt_pk_bf16_f32 v37, v38, v39
	v_lshlrev_b64 v[38:39], 12, v[56:57]
	v_cvt_pk_bf16_f32 v34, v34, v35
	v_cvt_pk_bf16_f32 v35, v40, v41
	v_lshl_add_u64 v[38:39], v[46:47], 0, v[38:39]
	global_store_dwordx4 v[38:39], v[34:37], off
	global_load_dwordx4 v[92:95], v[48:49], off offset:16
	global_load_dwordx4 v[132:135], v[48:49], off
	v_lshlrev_b32_e32 v38, 16, v44
	v_and_b32_e32 v39, 0xffff0000, v44
	v_lshlrev_b32_e32 v34, 16, v42
	v_mul_f32_e32 v34, 0xbfb8aa3b, v34
	v_exp_f32_e32 v34, v34
	v_and_b32_e32 v35, 0xffff0000, v42
	v_lshlrev_b32_e32 v36, 16, v43
	v_and_b32_e32 v37, 0xffff0000, v43
	v_add_f32_e32 v34, 1.0, v34
	v_rcp_f32_e32 v40, v34
	v_mul_f32_e32 v34, 0xbfb8aa3b, v35
	v_exp_f32_e32 v34, v34
	v_lshlrev_b32_e32 v56, 16, v45
	v_and_b32_e32 v57, 0xffff0000, v45
	v_and_b32_e32 v35, 0xffff0000, v29
	v_add_f32_e32 v34, 1.0, v34
	v_rcp_f32_e32 v41, v34
	v_mul_f32_e32 v34, 0xbfb8aa3b, v36
	v_exp_f32_e32 v34, v34
	v_lshlrev_b32_e32 v36, 16, v33
	v_lshlrev_b32_e32 v64, 16, v27
	v_and_b32_e32 v65, 0xffff0000, v27
	v_add_f32_e32 v34, 1.0, v34
	v_rcp_f32_e32 v42, v34
	v_mul_f32_e32 v34, 0xbfb8aa3b, v37
	v_exp_f32_e32 v34, v34
	v_and_b32_e32 v37, 0xffff0000, v33
	v_and_b32_e32 v27, 0xffff0000, v30
	v_pk_add_f32 v[26:27], v[68:69], v[26:27]
	v_add_f32_e32 v34, 1.0, v34
	v_rcp_f32_e32 v43, v34
	v_mul_f32_e32 v34, 0xbfb8aa3b, v38
	v_exp_f32_e32 v34, v34
	v_pk_add_f32 v[64:65], v[64:65], v[66:67]
	v_pk_mul_f32 v[30:31], v[26:27], v[26:27]
	v_pk_mul_f32 v[66:67], v[64:65], v[64:65]
	v_add_f32_e32 v34, 1.0, v34
	v_rcp_f32_e32 v44, v34
	v_mul_f32_e32 v34, 0xbfb8aa3b, v39
	v_exp_f32_e32 v34, v34
	v_add_f32_e32 v30, v30, v31
	v_add_f32_e32 v30, v66, v30
	v_add_f32_e32 v30, v67, v30
	v_add_f32_e32 v34, 1.0, v34
	v_rcp_f32_e32 v45, v34
	v_mul_f32_e32 v34, 0xbfb8aa3b, v56
	v_exp_f32_e32 v34, v34
	s_nop 0
	v_add_f32_e32 v34, 1.0, v34
	v_rcp_f32_e32 v56, v34
	v_mul_f32_e32 v34, 0xbfb8aa3b, v57
	v_exp_f32_e32 v34, v34
	s_nop 0
	v_add_f32_e32 v34, 1.0, v34
	v_rcp_f32_e32 v57, v34
	v_lshlrev_b32_e32 v34, 16, v29
	v_pk_add_f32 v[58:59], v[34:35], v[36:37]
	v_lshlrev_b32_e32 v34, 16, v28
	v_and_b32_e32 v35, 0xffff0000, v28
	v_lshlrev_b32_e32 v28, 16, v32
	v_and_b32_e32 v29, 0xffff0000, v32
	v_pk_add_f32 v[28:29], v[34:35], v[28:29]
	s_nop 0
	s_nop 0
	v_pk_mul_f32 v[62:63], v[28:29], v[28:29]
	v_pk_mul_f32 v[60:61], v[58:59], v[58:59]
	v_add_f32_e32 v30, v62, v30
	v_add_f32_e32 v30, v63, v30
	v_add_f32_e32 v30, v60, v30
	v_add_f32_e32 v30, v61, v30
	s_nop 1
	v_add_f32_dpp v30, v30, v30 quad_perm:[1,0,3,2] row_mask:0xf bank_mask:0xf bound_ctrl:1
	s_nop 1
	v_add_f32_dpp v30, v30, v30 quad_perm:[2,3,0,1] row_mask:0xf bank_mask:0xf bound_ctrl:1
	s_nop 1
	v_add_f32_dpp v30, v30, v30 row_half_mirror row_mask:0xf bank_mask:0xf bound_ctrl:1
	s_nop 1
	v_add_f32_dpp v30, v30, v30 row_mirror row_mask:0xf bank_mask:0xf bound_ctrl:1
	v_fmamk_f32 v30, v30, 0x3c000000, v233
	v_rsq_f32_e32 v30, v30
	s_nop 0
	v_pk_mul_f32 v[26:27], v[26:27], v[30:31] op_sel_hi:[1,0]
	v_pk_mul_f32 v[28:29], v[28:29], v[30:31] op_sel_hi:[1,0]
	s_waitcnt vmcnt(0)
	v_pk_mul_f32 v[26:27], v[132:133], v[26:27]
	v_pk_mul_f32 v[36:37], v[64:65], v[30:31] op_sel_hi:[1, 0]
	v_pk_mul_f32 v[30:31], v[58:59], v[30:31] op_sel_hi:[1,0]
	v_pk_mul_f32 v[28:29], v[92:93], v[28:29]
	v_pk_mul_f32 v[30:31], v[30:31], v[94:95]
	v_pk_mul_f32 v[36:37], v[134:135], v[36:37]
	v_pk_mul_f32 v[28:29], v[44:45], v[28:29]
	v_pk_mul_f32 v[30:31], v[56:57], v[30:31]
	v_pk_mul_f32 v[26:27], v[40:41], v[26:27]
	v_pk_mul_f32 v[36:37], v[42:43], v[36:37]
	v_cvt_pk_bf16_f32 v28, v28, v29
	v_cvt_pk_bf16_f32 v29, v30, v31
	v_lshlrev_b64 v[30:31], 12, v[54:55]
	v_cvt_pk_bf16_f32 v26, v26, v27
	v_cvt_pk_bf16_f32 v27, v36, v37
	v_lshl_add_u64 v[30:31], v[46:47], 0, v[30:31]
	global_store_dwordx4 v[30:31], v[26:29], off
	global_load_dwordx4 v[136:139], v[48:49], off offset:16
	global_load_dwordx4 v[140:143], v[48:49], off
	v_lshlrev_b32_e32 v32, 16, v24
	v_and_b32_e32 v24, 0xffff0000, v24
	v_lshlrev_b32_e32 v26, 16, v22
	v_and_b32_e32 v22, 0xffff0000, v22
	v_mul_f32_e32 v22, 0xbfb8aa3b, v22
	v_exp_f32_e32 v22, v22
	v_lshlrev_b32_e32 v27, 16, v23
	v_and_b32_e32 v23, 0xffff0000, v23
	v_lshlrev_b32_e32 v34, 16, v25
	v_add_f32_e32 v22, 1.0, v22
	v_rcp_f32_e32 v29, v22
	v_mul_f32_e32 v22, 0xbfb8aa3b, v27
	v_exp_f32_e32 v22, v22
	v_and_b32_e32 v25, 0xffff0000, v25
	v_mul_f32_e32 v26, 0xbfb8aa3b, v26
	v_exp_f32_e32 v26, v26
	v_add_f32_e32 v22, 1.0, v22
	v_rcp_f32_e32 v30, v22
	v_mul_f32_e32 v22, 0xbfb8aa3b, v23
	v_exp_f32_e32 v22, v22
	v_and_b32_e32 v23, 0xffff0000, v17
	v_add_f32_e32 v26, 1.0, v26
	v_rcp_f32_e32 v28, v26
	v_add_f32_e32 v22, 1.0, v22
	v_rcp_f32_e32 v31, v22
	v_mul_f32_e32 v22, 0xbfb8aa3b, v32
	v_exp_f32_e32 v22, v22
	v_lshlrev_b32_e32 v42, 16, v15
	v_and_b32_e32 v43, 0xffff0000, v15
	v_lshlrev_b32_e32 v54, 16, v14
	v_add_f32_e32 v22, 1.0, v22
	v_rcp_f32_e32 v32, v22
	v_mul_f32_e32 v22, 0xbfb8aa3b, v24
	v_exp_f32_e32 v22, v22
	v_lshlrev_b32_e32 v24, 16, v21
	v_and_b32_e32 v55, 0xffff0000, v14
	v_lshlrev_b32_e32 v14, 16, v18
	v_add_f32_e32 v22, 1.0, v22
	v_rcp_f32_e32 v33, v22
	v_mul_f32_e32 v22, 0xbfb8aa3b, v34
	v_exp_f32_e32 v22, v22
	v_and_b32_e32 v15, 0xffff0000, v18
	v_lshlrev_b32_e32 v44, 16, v19
	v_and_b32_e32 v45, 0xffff0000, v19
	v_add_f32_e32 v22, 1.0, v22
	v_rcp_f32_e32 v34, v22
	v_mul_f32_e32 v22, 0xbfb8aa3b, v25
	v_exp_f32_e32 v22, v22
	v_and_b32_e32 v25, 0xffff0000, v21
	v_pk_add_f32 v[14:15], v[54:55], v[14:15]
	v_pk_add_f32 v[42:43], v[42:43], v[44:45]
	v_add_f32_e32 v22, 1.0, v22
	v_rcp_f32_e32 v35, v22
	v_lshlrev_b32_e32 v22, 16, v17
	v_pk_add_f32 v[36:37], v[22:23], v[24:25]
	v_lshlrev_b32_e32 v22, 16, v16
	v_and_b32_e32 v23, 0xffff0000, v16
	v_lshlrev_b32_e32 v16, 16, v20
	v_and_b32_e32 v17, 0xffff0000, v20
	v_pk_add_f32 v[16:17], v[22:23], v[16:17]
	s_nop 0
	s_nop 0
	v_pk_mul_f32 v[18:19], v[14:15], v[14:15]
	v_pk_mul_f32 v[44:45], v[42:43], v[42:43]
	v_add_f32_e32 v18, v18, v19
	v_add_f32_e32 v18, v44, v18
	v_pk_mul_f32 v[40:41], v[16:17], v[16:17]
	v_add_f32_e32 v18, v45, v18
	v_add_f32_e32 v18, v40, v18
	v_pk_mul_f32 v[38:39], v[36:37], v[36:37]
	v_add_f32_e32 v18, v41, v18
	v_add_f32_e32 v18, v38, v18
	v_add_f32_e32 v18, v39, v18
	s_nop 1
	v_add_f32_dpp v18, v18, v18 quad_perm:[1,0,3,2] row_mask:0xf bank_mask:0xf bound_ctrl:1
	s_nop 1
	v_add_f32_dpp v18, v18, v18 quad_perm:[2,3,0,1] row_mask:0xf bank_mask:0xf bound_ctrl:1
	s_nop 1
	v_add_f32_dpp v18, v18, v18 row_half_mirror row_mask:0xf bank_mask:0xf bound_ctrl:1
	s_nop 1
	v_add_f32_dpp v18, v18, v18 row_mirror row_mask:0xf bank_mask:0xf bound_ctrl:1
	v_fmamk_f32 v18, v18, 0x3c000000, v233
	v_rsq_f32_e32 v18, v18
	s_nop 0
	v_pk_mul_f32 v[14:15], v[14:15], v[18:19] op_sel_hi:[1,0]
	v_pk_mul_f32 v[16:17], v[16:17], v[18:19] op_sel_hi:[1,0]
	s_waitcnt vmcnt(0)
	v_pk_mul_f32 v[14:15], v[140:141], v[14:15]
	v_pk_mul_f32 v[24:25], v[42:43], v[18:19] op_sel_hi:[1, 0]
	v_pk_mul_f32 v[18:19], v[36:37], v[18:19] op_sel_hi:[1,0]
	v_pk_mul_f32 v[16:17], v[136:137], v[16:17]
	v_pk_mul_f32 v[18:19], v[18:19], v[138:139]
	v_pk_mul_f32 v[24:25], v[142:143], v[24:25]
	v_pk_mul_f32 v[16:17], v[32:33], v[16:17]
	v_pk_mul_f32 v[18:19], v[34:35], v[18:19]
	v_pk_mul_f32 v[14:15], v[28:29], v[14:15]
	v_pk_mul_f32 v[24:25], v[30:31], v[24:25]
	v_cvt_pk_bf16_f32 v16, v16, v17
	v_cvt_pk_bf16_f32 v17, v18, v19
	v_lshlrev_b64 v[18:19], 12, v[52:53]
	v_cvt_pk_bf16_f32 v14, v14, v15
	v_cvt_pk_bf16_f32 v15, v24, v25
	v_lshl_add_u64 v[18:19], v[46:47], 0, v[18:19]
	global_store_dwordx4 v[18:19], v[14:17], off
	global_load_dwordx4 v[144:147], v[48:49], off offset:16
	global_load_dwordx4 v[148:151], v[48:49], off
	v_lshlrev_b32_e32 v20, 16, v12
	v_and_b32_e32 v12, 0xffff0000, v12
	v_lshlrev_b32_e32 v14, 16, v10
	v_and_b32_e32 v10, 0xffff0000, v10
	v_mul_f32_e32 v10, 0xbfb8aa3b, v10
	v_exp_f32_e32 v10, v10
	v_lshlrev_b32_e32 v15, 16, v11
	v_and_b32_e32 v11, 0xffff0000, v11
	v_lshlrev_b32_e32 v22, 16, v13
	v_add_f32_e32 v10, 1.0, v10
	v_rcp_f32_e32 v17, v10
	v_mul_f32_e32 v10, 0xbfb8aa3b, v15
	v_exp_f32_e32 v10, v10
	v_and_b32_e32 v13, 0xffff0000, v13
	v_mul_f32_e32 v14, 0xbfb8aa3b, v14
	v_exp_f32_e32 v14, v14
	v_add_f32_e32 v10, 1.0, v10
	v_rcp_f32_e32 v18, v10
	v_mul_f32_e32 v10, 0xbfb8aa3b, v11
	v_exp_f32_e32 v10, v10
	v_and_b32_e32 v11, 0xffff0000, v5
	v_add_f32_e32 v14, 1.0, v14
	v_rcp_f32_e32 v16, v14
	v_add_f32_e32 v10, 1.0, v10
	v_rcp_f32_e32 v19, v10
	v_mul_f32_e32 v10, 0xbfb8aa3b, v20
	v_exp_f32_e32 v10, v10
	v_lshlrev_b32_e32 v30, 16, v3
	v_and_b32_e32 v31, 0xffff0000, v3
	v_lshlrev_b32_e32 v34, 16, v2
	v_add_f32_e32 v10, 1.0, v10
	v_rcp_f32_e32 v20, v10
	v_mul_f32_e32 v10, 0xbfb8aa3b, v12
	v_exp_f32_e32 v10, v10
	v_lshlrev_b32_e32 v12, 16, v9
	v_and_b32_e32 v35, 0xffff0000, v2
	v_lshlrev_b32_e32 v2, 16, v6
	v_add_f32_e32 v10, 1.0, v10
	v_rcp_f32_e32 v21, v10
	v_mul_f32_e32 v10, 0xbfb8aa3b, v22
	v_exp_f32_e32 v10, v10
	v_and_b32_e32 v3, 0xffff0000, v6
	v_lshlrev_b32_e32 v32, 16, v7
	v_and_b32_e32 v33, 0xffff0000, v7
	v_add_f32_e32 v10, 1.0, v10
	v_rcp_f32_e32 v22, v10
	v_mul_f32_e32 v10, 0xbfb8aa3b, v13
	v_exp_f32_e32 v10, v10
	v_and_b32_e32 v13, 0xffff0000, v9
	v_pk_add_f32 v[2:3], v[34:35], v[2:3]
	v_pk_add_f32 v[30:31], v[30:31], v[32:33]
	v_add_f32_e32 v10, 1.0, v10
	v_rcp_f32_e32 v23, v10
	v_lshlrev_b32_e32 v10, 16, v5
	v_pk_add_f32 v[24:25], v[10:11], v[12:13]
	v_lshlrev_b32_e32 v10, 16, v4
	v_and_b32_e32 v11, 0xffff0000, v4
	v_lshlrev_b32_e32 v4, 16, v8
	v_and_b32_e32 v5, 0xffff0000, v8
	v_pk_add_f32 v[4:5], v[10:11], v[4:5]
	s_nop 0
	s_nop 0
	v_pk_mul_f32 v[6:7], v[2:3], v[2:3]
	v_pk_mul_f32 v[32:33], v[30:31], v[30:31]
	v_add_f32_e32 v6, v6, v7
	v_add_f32_e32 v6, v32, v6
	v_pk_mul_f32 v[28:29], v[4:5], v[4:5]
	v_add_f32_e32 v6, v33, v6
	v_add_f32_e32 v6, v28, v6
	v_pk_mul_f32 v[26:27], v[24:25], v[24:25]
	v_add_f32_e32 v6, v29, v6
	v_add_f32_e32 v6, v26, v6
	v_add_f32_e32 v6, v27, v6
	s_nop 1
	v_add_f32_dpp v6, v6, v6 quad_perm:[1,0,3,2] row_mask:0xf bank_mask:0xf bound_ctrl:1
	s_nop 1
	v_add_f32_dpp v6, v6, v6 quad_perm:[2,3,0,1] row_mask:0xf bank_mask:0xf bound_ctrl:1
	s_nop 1
	v_add_f32_dpp v6, v6, v6 row_half_mirror row_mask:0xf bank_mask:0xf bound_ctrl:1
	s_nop 1
	v_add_f32_dpp v6, v6, v6 row_mirror row_mask:0xf bank_mask:0xf bound_ctrl:1
	v_fmamk_f32 v6, v6, 0x3c000000, v233
	v_rsq_f32_e32 v6, v6
	s_nop 0
	v_pk_mul_f32 v[2:3], v[2:3], v[6:7] op_sel_hi:[1,0]
	v_pk_mul_f32 v[4:5], v[4:5], v[6:7] op_sel_hi:[1,0]
	s_waitcnt vmcnt(0)
	v_pk_mul_f32 v[2:3], v[148:149], v[2:3]
	v_pk_mul_f32 v[12:13], v[30:31], v[6:7] op_sel_hi:[1, 0]
	v_pk_mul_f32 v[6:7], v[24:25], v[6:7] op_sel_hi:[1,0]
	v_pk_mul_f32 v[4:5], v[144:145], v[4:5]
	v_pk_mul_f32 v[6:7], v[6:7], v[146:147]
	v_pk_mul_f32 v[12:13], v[150:151], v[12:13]
	v_pk_mul_f32 v[4:5], v[20:21], v[4:5]
	v_pk_mul_f32 v[6:7], v[22:23], v[6:7]
	v_pk_mul_f32 v[2:3], v[16:17], v[2:3]
	v_pk_mul_f32 v[12:13], v[18:19], v[12:13]
	v_cvt_pk_bf16_f32 v4, v4, v5
	v_cvt_pk_bf16_f32 v5, v6, v7
	v_lshlrev_b64 v[6:7], 12, v[50:51]
	v_cvt_pk_bf16_f32 v2, v2, v3
	v_cvt_pk_bf16_f32 v3, v12, v13
	v_lshl_add_u64 v[6:7], v[46:47], 0, v[6:7]
	global_store_dwordx4 v[6:7], v[2:5], off
	v_mov_b32_e32 v11, v147
	v_mov_b32_e32 v72, v88
	v_mov_b32_e32 v73, v89
	v_mov_b32_e32 v74, v90
	v_mov_b32_e32 v75, v91
	s_cbranch_vccnz .LBB0_463
	s_branch .LBB0_403

.LBB0_616:
	global_load_dwordx4 v[2:5], v[10:11], off offset:16
	global_load_dwordx4 v[6:9], v[10:11], off
	v_lshl_add_u64 v[12:13], s[8:9], 0, v[0:1]
	v_add_co_u32_e32 v26, vcc, 0x49200000, v12
	v_lshl_add_u64 v[14:15], s[6:7], 0, v[0:1]
	s_nop 0
	v_addc_co_u32_e32 v27, vcc, 0, v13, vcc
	global_load_dwordx4 v[50:53], v[26:27], off
	v_add_co_u32_e32 v30, vcc, 0x4a600000, v12
	v_lshl_add_u64 v[18:19], s[2:3], 0, v[0:1]
	s_mov_b32 s1, 0x25e00000
	v_addc_co_u32_e32 v31, vcc, 0, v13, vcc
	global_load_dwordx4 v[22:25], v[30:31], off
	v_add_co_u32_e64 v28, s[4:5], s1, v18
	v_add_co_u32_e32 v32, vcc, 0x1fa01000, v14
	s_nop 0
	s_nop 0
	v_addc_co_u32_e64 v29, s[4:5], 0, v19, s[4:5]
	s_nop 0
	s_nop 0
	v_addc_co_u32_e32 v33, vcc, 0, v15, vcc
	global_load_dwordx4 v[12:15], v[32:33], off offset:2048
	s_add_i32 s0, s0, s82
	s_add_u32 s2, s2, s56
	s_addc_u32 s3, s3, s57
	s_add_u32 s6, s6, s10
	s_addc_u32 s7, s7, s11
	s_add_u32 s8, s8, s28
	s_addc_u32 s9, s9, s29
	s_cmpk_gt_i32 s0, 0x27ff
	s_waitcnt vmcnt(5)
	s_waitcnt vmcnt(2)
	v_lshlrev_b32_e32 v34, 16, v53
	v_and_b32_e32 v35, 0xffff0000, v53
	v_lshlrev_b32_e32 v36, 16, v52
	v_and_b32_e32 v37, 0xffff0000, v52
	v_lshlrev_b32_e32 v20, 16, v51
	v_and_b32_e32 v21, 0xffff0000, v51
	v_lshlrev_b32_e32 v38, 16, v50
	v_and_b32_e32 v39, 0xffff0000, v50
	s_waitcnt vmcnt(1)
	v_lshlrev_b32_e32 v18, 16, v25
	v_and_b32_e32 v19, 0xffff0000, v25
	v_lshlrev_b32_e32 v40, 16, v24
	v_and_b32_e32 v41, 0xffff0000, v24
	v_lshlrev_b32_e32 v24, 16, v23
	v_and_b32_e32 v25, 0xffff0000, v23
	v_lshlrev_b32_e32 v42, 16, v22
	v_and_b32_e32 v43, 0xffff0000, v22
	s_waitcnt vmcnt(0)
	v_lshlrev_b32_e32 v17, 16, v12
	v_and_b32_e32 v22, 0xffff0000, v12
	v_lshlrev_b32_e32 v23, 16, v13
	v_and_b32_e32 v44, 0xffff0000, v13
	v_lshlrev_b32_e32 v45, 16, v14
	v_pk_add_f32 v[12:13], v[34:35], v[18:19]
	v_pk_add_f32 v[18:19], v[20:21], v[24:25]
	v_pk_add_f32 v[20:21], v[38:39], v[42:43]
	v_and_b32_e32 v46, 0xffff0000, v14
	v_lshlrev_b32_e32 v47, 16, v15
	v_and_b32_e32 v48, 0xffff0000, v15
	v_pk_add_f32 v[14:15], v[36:37], v[40:41]
	v_mul_f32_e32 v17, 0xbfb8aa3b, v17
	v_mul_f32_e32 v41, 0xbfb8aa3b, v45
	v_pk_mul_f32 v[36:37], v[20:21], v[20:21]
	v_pk_mul_f32 v[34:35], v[18:19], v[18:19]
	v_exp_f32_e32 v17, v17
	v_exp_f32_e32 v41, v41
	v_add_f32_e32 v36, v36, v37
	v_add_f32_e32 v34, v34, v36
	v_pk_mul_f32 v[24:25], v[14:15], v[14:15]
	v_add_f32_e32 v34, v35, v34
	v_add_f32_e32 v24, v24, v34
	v_mul_f32_e32 v38, 0xbfb8aa3b, v22
	v_mul_f32_e32 v39, 0xbfb8aa3b, v23
	v_pk_mul_f32 v[22:23], v[12:13], v[12:13]
	v_add_f32_e32 v17, 1.0, v17
	v_add_f32_e32 v37, 1.0, v41
	v_add_f32_e32 v41, v25, v24
	v_rcp_f32_e32 v24, v17
	v_add_f32_e32 v17, v22, v41
	v_add_f32_e32 v17, v23, v17
	v_mul_f32_e32 v40, 0xbfb8aa3b, v44
	v_mul_f32_e32 v42, 0xbfb8aa3b, v46
	v_add_f32_dpp v17, v17, v17 quad_perm:[1,0,3,2] row_mask:0xf bank_mask:0xf bound_ctrl:1
	v_mul_f32_e32 v43, 0xbfb8aa3b, v47
	v_mul_f32_e32 v44, 0xbfb8aa3b, v48
	v_add_f32_dpp v17, v17, v17 quad_perm:[2,3,0,1] row_mask:0xf bank_mask:0xf bound_ctrl:1
	v_exp_f32_e32 v38, v38
	v_exp_f32_e32 v39, v39
	v_exp_f32_e32 v40, v40
	v_exp_f32_e32 v42, v42
	v_exp_f32_e32 v43, v43
	v_exp_f32_e32 v44, v44
	v_add_f32_dpp v17, v17, v17 row_half_mirror row_mask:0xf bank_mask:0xf bound_ctrl:1
	v_add_f32_e32 v34, 1.0, v38
	v_add_f32_e32 v35, 1.0, v39
	v_add_f32_dpp v17, v17, v17 row_mirror row_mask:0xf bank_mask:0xf bound_ctrl:1
	v_fmamk_f32 v17, v17, 0x3c000000, v233
	v_rsq_f32_e32 v22, v17
	v_add_f32_e32 v36, 1.0, v40
	v_add_f32_e32 v38, 1.0, v42
	v_add_f32_e32 v39, 1.0, v43
	v_add_f32_e32 v40, 1.0, v44
	v_rcp_f32_e32 v25, v34
	v_rcp_f32_e32 v34, v35
	v_rcp_f32_e32 v35, v36
	v_rcp_f32_e32 v36, v37
	v_rcp_f32_e32 v37, v38
	v_rcp_f32_e32 v38, v39
	v_rcp_f32_e32 v39, v40
	v_pk_mul_f32 v[20:21], v[20:21], v[22:23] op_sel_hi:[1,0]
	v_pk_mul_f32 v[18:19], v[18:19], v[22:23] op_sel_hi:[1,0]
	v_pk_mul_f32 v[14:15], v[14:15], v[22:23] op_sel_hi:[1,0]
	v_pk_mul_f32 v[12:13], v[12:13], v[22:23] op_sel_hi:[1,0]
	v_pk_mul_f32 v[6:7], v[6:7], v[20:21]
	v_pk_mul_f32 v[8:9], v[8:9], v[18:19]
	v_pk_mul_f32 v[2:3], v[2:3], v[14:15]
	v_pk_mul_f32 v[4:5], v[4:5], v[12:13]
	v_pk_mul_f32 v[6:7], v[24:25], v[6:7]
	v_pk_mul_f32 v[8:9], v[34:35], v[8:9]
	v_pk_mul_f32 v[12:13], v[36:37], v[2:3]
	v_pk_mul_f32 v[14:15], v[38:39], v[4:5]
	v_cvt_pk_bf16_f32 v2, v6, v7
	v_cvt_pk_bf16_f32 v3, v8, v9
	v_cvt_pk_bf16_f32 v4, v12, v13
	v_cvt_pk_bf16_f32 v5, v14, v15
	global_store_dwordx4 v[28:29], v[2:5], off
	global_load_dwordx4 v[2:5], v[26:27], off offset:1024
	global_load_dwordx4 v[6:9], v[30:31], off offset:1024
	global_load_dwordx4 v[12:15], v[32:33], off offset:3072
	global_load_dwordx4 v[18:21], v[10:11], off offset:16
	global_load_dwordx4 v[22:25], v[10:11], off
	s_nop 0
	s_nop 0
	s_nop 0
	s_nop 0
	s_nop 0
	s_waitcnt vmcnt(4)
	v_lshlrev_b32_e32 v26, 16, v4
	v_and_b32_e32 v27, 0xffff0000, v4
	s_waitcnt vmcnt(2)
	v_lshlrev_b32_e32 v17, 16, v12
	v_and_b32_e32 v34, 0xffff0000, v12
	v_lshlrev_b32_e32 v35, 16, v13
	v_and_b32_e32 v36, 0xffff0000, v13
	v_lshlrev_b32_e32 v37, 16, v14
	v_and_b32_e32 v38, 0xffff0000, v14
	v_lshlrev_b32_e32 v39, 16, v15
	v_and_b32_e32 v40, 0xffff0000, v15
	v_lshlrev_b32_e32 v12, 16, v5
	v_and_b32_e32 v13, 0xffff0000, v5
	v_lshlrev_b32_e32 v14, 16, v9
	v_and_b32_e32 v15, 0xffff0000, v9
	v_lshlrev_b32_e32 v4, 16, v8
	v_and_b32_e32 v5, 0xffff0000, v8
	v_lshlrev_b32_e32 v8, 16, v3
	v_and_b32_e32 v9, 0xffff0000, v3
	v_lshlrev_b32_e32 v32, 16, v2
	v_and_b32_e32 v33, 0xffff0000, v2
	v_lshlrev_b32_e32 v2, 16, v6
	v_and_b32_e32 v3, 0xffff0000, v6
	v_lshlrev_b32_e32 v30, 16, v7
	v_and_b32_e32 v31, 0xffff0000, v7
	v_pk_add_f32 v[2:3], v[32:33], v[2:3]
	v_pk_add_f32 v[8:9], v[8:9], v[30:31]
	v_pk_mul_f32 v[30:31], v[2:3], v[2:3]
	v_pk_add_f32 v[4:5], v[26:27], v[4:5]
	v_pk_mul_f32 v[26:27], v[8:9], v[8:9]
	v_add_f32_e32 v30, v30, v31
	v_add_f32_e32 v26, v26, v30
	v_pk_add_f32 v[6:7], v[12:13], v[14:15]
	v_pk_mul_f32 v[14:15], v[4:5], v[4:5]
	v_add_f32_e32 v26, v27, v26
	v_add_f32_e32 v14, v14, v26
	v_pk_mul_f32 v[12:13], v[6:7], v[6:7]
	v_add_f32_e32 v14, v15, v14
	v_add_f32_e32 v12, v12, v14
	v_add_f32_e32 v12, v13, v12
	v_mul_f32_e32 v17, 0xbfb8aa3b, v17
	v_mul_f32_e32 v34, 0xbfb8aa3b, v34
	v_add_f32_dpp v12, v12, v12 quad_perm:[1,0,3,2] row_mask:0xf bank_mask:0xf bound_ctrl:1
	v_mul_f32_e32 v35, 0xbfb8aa3b, v35
	v_mul_f32_e32 v36, 0xbfb8aa3b, v36
	v_mul_f32_e32 v37, 0xbfb8aa3b, v37
	v_mul_f32_e32 v38, 0xbfb8aa3b, v38
	v_mul_f32_e32 v39, 0xbfb8aa3b, v39
	v_mul_f32_e32 v40, 0xbfb8aa3b, v40
	v_add_f32_dpp v12, v12, v12 quad_perm:[2,3,0,1] row_mask:0xf bank_mask:0xf bound_ctrl:1
	v_exp_f32_e32 v17, v17
	v_exp_f32_e32 v32, v34
	v_exp_f32_e32 v33, v35
	v_exp_f32_e32 v34, v36
	v_exp_f32_e32 v35, v37
	v_exp_f32_e32 v36, v38
	v_exp_f32_e32 v37, v39
	v_exp_f32_e32 v38, v40
	v_add_f32_dpp v12, v12, v12 row_half_mirror row_mask:0xf bank_mask:0xf bound_ctrl:1
	v_add_f32_e32 v17, 1.0, v17
	v_add_f32_e32 v27, 1.0, v32
	v_add_f32_dpp v12, v12, v12 row_mirror row_mask:0xf bank_mask:0xf bound_ctrl:1
	v_fmamk_f32 v12, v12, 0x3c000000, v233
	v_rsq_f32_e32 v12, v12
	v_add_f32_e32 v30, 1.0, v33
	v_add_f32_e32 v31, 1.0, v34
	v_add_f32_e32 v32, 1.0, v35
	v_add_f32_e32 v33, 1.0, v36
	v_add_f32_e32 v34, 1.0, v37
	v_add_f32_e32 v35, 1.0, v38
	v_rcp_f32_e32 v26, v17
	v_rcp_f32_e32 v27, v27
	v_rcp_f32_e32 v30, v30
	v_rcp_f32_e32 v31, v31
	v_rcp_f32_e32 v32, v32
	v_rcp_f32_e32 v33, v33
	v_rcp_f32_e32 v34, v34
	v_rcp_f32_e32 v35, v35
	v_pk_mul_f32 v[2:3], v[2:3], v[12:13] op_sel_hi:[1,0]
	v_pk_mul_f32 v[8:9], v[8:9], v[12:13] op_sel_hi:[1,0]
	v_pk_mul_f32 v[4:5], v[4:5], v[12:13] op_sel_hi:[1,0]
	v_pk_mul_f32 v[6:7], v[6:7], v[12:13] op_sel_hi:[1,0]
	s_waitcnt vmcnt(0)
	v_pk_mul_f32 v[2:3], v[22:23], v[2:3]
	v_pk_mul_f32 v[8:9], v[24:25], v[8:9]
	v_pk_mul_f32 v[4:5], v[18:19], v[4:5]
	v_pk_mul_f32 v[6:7], v[20:21], v[6:7]
	v_pk_mul_f32 v[2:3], v[26:27], v[2:3]
	v_pk_mul_f32 v[8:9], v[30:31], v[8:9]
	v_pk_mul_f32 v[4:5], v[32:33], v[4:5]
	v_pk_mul_f32 v[6:7], v[34:35], v[6:7]
	v_cvt_pk_bf16_f32 v2, v2, v3
	v_cvt_pk_bf16_f32 v3, v8, v9
	v_cvt_pk_bf16_f32 v4, v4, v5
	v_cvt_pk_bf16_f32 v5, v6, v7
	global_store_dwordx4 v[28:29], v[2:5], off offset:1024
	s_cbranch_scc0 .LBB0_616

.LBB0_655:
	s_lshr_b32 s30, s29, 6
	s_and_b32 s31, s16, 63
	v_mov_b32_e32 v0, s31
	v_mov_b32_e32 v52, s30
	v_cndmask_b32_e64 v0, v0, v52, s[6:7]
	v_lshl_or_b32 v58, v0, 5, v70
	v_lshlrev_b32_e32 v0, 3, v58
	v_lshl_add_u64 v[66:67], s[0:1], 0, v[0:1]
	v_or_b32_e32 v0, 2, v58
	v_lshl_add_u64 v[68:69], v[0:1], 3, s[0:1]
	v_or_b32_e32 v0, 4, v58
	v_lshl_add_u64 v[62:63], v[0:1], 3, s[0:1]
	v_or_b32_e32 v0, 6, v58
	v_lshl_add_u64 v[64:65], v[0:1], 3, s[0:1]
	v_or_b32_e32 v0, 8, v58
	v_lshl_add_u64 v[54:55], v[0:1], 3, s[0:1]
	v_or_b32_e32 v0, 10, v58
	v_lshl_add_u64 v[60:61], v[0:1], 3, s[0:1]
	v_or_b32_e32 v0, 12, v58
	v_lshl_add_u64 v[52:53], v[0:1], 3, s[0:1]
	v_or_b32_e32 v0, 14, v58
	s_andn2_b64 vcc, exec, s[12:13]
	v_lshl_add_u64 v[58:59], v[0:1], 3, s[0:1]
	s_cbranch_vccnz .LBB0_657
	global_load_dwordx2 v[80:81], v[66:67], off
	global_load_dwordx2 v[82:83], v[68:69], off
	s_nop 0
	v_mov_b32_dpp v72, v22 quad_perm:[2,3,0,1] row_mask:0xf bank_mask:0xf bound_ctrl:1
	v_mov_b32_dpp v73, v23 quad_perm:[2,3,0,1] row_mask:0xf bank_mask:0xf bound_ctrl:1
	v_mov_b32_dpp v74, v24 quad_perm:[2,3,0,1] row_mask:0xf bank_mask:0xf bound_ctrl:1
	v_mov_b32_dpp v75, v25 quad_perm:[2,3,0,1] row_mask:0xf bank_mask:0xf bound_ctrl:1
	v_mov_b32_dpp v76, v18 quad_perm:[2,3,0,1] row_mask:0xf bank_mask:0xf bound_ctrl:1
	v_mov_b32_dpp v77, v19 quad_perm:[2,3,0,1] row_mask:0xf bank_mask:0xf bound_ctrl:1
	v_mov_b32_dpp v78, v20 quad_perm:[2,3,0,1] row_mask:0xf bank_mask:0xf bound_ctrl:1
	v_mov_b32_dpp v79, v21 quad_perm:[2,3,0,1] row_mask:0xf bank_mask:0xf bound_ctrl:1
	v_lshlrev_b32_e32 v0, 1, v26
	s_waitcnt vmcnt(2)
	s_waitcnt vmcnt(1)
	v_mov_b32_e32 v84, v81
	s_waitcnt vmcnt(0)
	v_mov_b32_e32 v85, v83
	v_pk_mul_f32 v[72:73], v[84:85], v[72:73]
	v_mov_b32_e32 v81, v82
	v_cndmask_b32_e64 v73, v73, -v73, s[10:11]
	v_cndmask_b32_e64 v72, v72, -v72, s[10:11]
	v_pk_fma_f32 v[22:23], v[80:81], v[22:23], v[72:73]
	global_load_dwordx2 v[72:73], v[62:63], off
	global_load_dwordx2 v[80:81], v[64:65], off
	s_nop 0
	s_waitcnt vmcnt(1)
	v_mov_b32_e32 v82, v73
	s_waitcnt vmcnt(0)
	v_mov_b32_e32 v83, v81
	v_pk_mul_f32 v[74:75], v[82:83], v[74:75]
	v_mov_b32_e32 v73, v80
	v_cndmask_b32_e64 v75, v75, -v75, s[10:11]
	v_cndmask_b32_e64 v74, v74, -v74, s[10:11]
	v_pk_fma_f32 v[24:25], v[72:73], v[24:25], v[74:75]
	global_load_dwordx2 v[72:73], v[54:55], off
	global_load_dwordx2 v[74:75], v[60:61], off
	s_nop 0
	s_waitcnt vmcnt(1)
	v_mov_b32_e32 v80, v73
	s_waitcnt vmcnt(0)
	v_mov_b32_e32 v81, v75
	v_pk_mul_f32 v[76:77], v[80:81], v[76:77]
	v_mov_b32_e32 v73, v74
	v_cndmask_b32_e64 v75, v77, -v77, s[10:11]
	v_cndmask_b32_e64 v74, v76, -v76, s[10:11]
	v_pk_fma_f32 v[72:73], v[72:73], v[18:19], v[74:75]
	global_load_dwordx2 v[18:19], v[52:53], off
	global_load_dwordx2 v[74:75], v[58:59], off
	s_nop 0
	s_waitcnt vmcnt(1)
	v_mov_b32_e32 v76, v19
	s_waitcnt vmcnt(0)
	v_mov_b32_e32 v77, v75
	v_pk_mul_f32 v[76:77], v[76:77], v[78:79]
	v_mov_b32_e32 v19, v74
	v_cndmask_b32_e64 v75, v77, -v77, s[10:11]
	v_cndmask_b32_e64 v74, v76, -v76, s[10:11]
	v_pk_fma_f32 v[74:75], v[18:19], v[20:21], v[74:75]
	v_cvt_pk_bf16_f32 v18, v22, v23
	v_cvt_pk_bf16_f32 v19, v24, v25
	v_cvt_pk_bf16_f32 v20, v72, v73
	v_cvt_pk_bf16_f32 v21, v74, v75
	global_store_dwordx4 v0, v[18:21], s[24:25]

.LBB0_819:
	s_add_u32 s0, s8, s42
	s_addc_u32 s1, s9, s43
	global_load_dword v2, v171, s[0:1]
	global_load_dword v3, v171, s[0:1] offset:256
	global_load_dword v175, v171, s[0:1] offset:512
	global_load_dword v183, v171, s[0:1] offset:768
	s_nop 0
	s_waitcnt vmcnt(4)
	s_waitcnt vmcnt(2)
	v_mul_f32_e32 v4, v2, v3
	s_nop 1
	v_mov_b32_dpp v4, v4 quad_perm:[1,0,3,2] row_mask:0xf bank_mask:0xf bound_ctrl:1
	v_fmac_f32_e32 v4, v2, v3
	s_nop 1
	v_add_f32_dpp v2, v4, v4 quad_perm:[2,3,0,1] row_mask:0xf bank_mask:0xf bound_ctrl:1
	s_nop 1
	v_add_f32_dpp v2, v2, v2 row_half_mirror row_mask:0xf bank_mask:0xf bound_ctrl:1
	s_nop 1
	v_add_f32_dpp v2, v2, v2 row_mirror row_mask:0xf bank_mask:0xf bound_ctrl:1
	ds_swizzle_b32 v3, v2 offset:swizzle(SWAP,16)
	s_waitcnt lgkmcnt(0)
	v_add_f32_e32 v2, v2, v3
	v_mov_b32_e32 v3, v2
	s_nop 1
	v_permlane32_swap_b32_e32 v2, v3
	v_add_f32_e32 v2, v2, v3
	s_nop 0
	s_nop 0
	v_mul_f32_e32 v2, 0x3fb8aa3b, v2
	v_exp_f32_e32 v2, v2
	s_waitcnt vmcnt(0)
	v_mul_f32_e32 v5, v175, v183
	s_nop 1
	v_mov_b32_dpp v5, v5 quad_perm:[1,0,3,2] row_mask:0xf bank_mask:0xf bound_ctrl:1
	v_fmac_f32_e32 v5, v175, v183
	s_nop 1
	v_add_f32_dpp v175, v5, v5 quad_perm:[2,3,0,1] row_mask:0xf bank_mask:0xf bound_ctrl:1
	s_nop 1
	v_add_f32_dpp v175, v175, v175 row_half_mirror row_mask:0xf bank_mask:0xf bound_ctrl:1
	s_nop 1
	v_add_f32_dpp v175, v175, v175 row_mirror row_mask:0xf bank_mask:0xf bound_ctrl:1
	ds_swizzle_b32 v4, v175 offset:swizzle(SWAP, 16)
	s_waitcnt lgkmcnt(0)
	v_add_f32_e32 v175, v175, v4
	v_mov_b32_e32 v4, v175
	s_nop 1
	v_permlane32_swap_b32_e32 v175, v4
	v_add_f32_e32 v175, v175, v4
	v_mul_f32_e32 v175, 0x3fb8aa3b, v175
	v_exp_f32_e32 v175, v175
	s_nop 0
	v_sub_f32_e32 v2, v2, v175
	v_add_f32_e32 v2, v169, v2
	v_div_scale_f32 v3, s[0:1], v0, v0, v2
	v_rcp_f32_e32 v4, v3
	s_lshl_b64 s[0:1], s[30:31], 2
	s_add_u32 s0, s10, s0
	s_addc_u32 s1, s11, s1
	v_fma_f32 v5, -v3, v4, 1.0
	v_fmac_f32_e32 v4, v5, v4
	v_div_scale_f32 v5, vcc, v2, v0, v2
	v_mul_f32_e32 v6, v5, v4
	v_fma_f32 v7, -v3, v6, v5
	v_fmac_f32_e32 v6, v7, v4
	v_fma_f32 v3, -v3, v6, v5
	v_div_fmas_f32 v3, v3, v4, v6
	v_div_fixup_f32 v14, v3, v0, v2
	v_add_u32_e32 v0, s19, v167
	ds_read_b128 v[152:155], v0 offset:53248
	ds_read_b128 v[132:135], v0 offset:54272
	ds_read_b128 v[120:123], v0 offset:55296
	ds_read_b128 v[108:111], v0 offset:56320
	ds_read_b128 v[96:99], v0 offset:57344
	ds_read_b128 v[84:87], v0 offset:58368
	ds_read_b128 v[6:9], v0 offset:59392
	ds_read_b128 v[2:5], v0 offset:60416
	v_lshlrev_b32_e32 v0, 2, v180
	global_load_dwordx4 v[160:163], v0, s[0:1]
	global_load_dwordx4 v[156:159], v0, s[0:1] offset:32
	global_load_dwordx4 v[148:151], v0, s[0:1] offset:64
	global_load_dwordx4 v[144:147], v0, s[0:1] offset:96
	global_load_dwordx4 v[140:143], v0, s[0:1] offset:128
	global_load_dwordx4 v[136:139], v0, s[0:1] offset:160
	global_load_dwordx4 v[128:131], v0, s[0:1] offset:192
	global_load_dwordx4 v[124:127], v0, s[0:1] offset:224
	global_load_dwordx4 v[116:119], v0, s[0:1] offset:256
	global_load_dwordx4 v[112:115], v0, s[0:1] offset:288
	global_load_dwordx4 v[104:107], v0, s[0:1] offset:320
	global_load_dwordx4 v[100:103], v0, s[0:1] offset:352
	global_load_dwordx4 v[92:95], v0, s[0:1] offset:384
	global_load_dwordx4 v[88:91], v0, s[0:1] offset:416
	global_load_dwordx4 v[80:83], v0, s[0:1] offset:448
	global_load_dwordx4 v[10:13], v0, s[0:1] offset:480
	s_nop 0
	s_nop 0
	s_nop 0
	s_nop 0
	s_nop 0
	s_nop 0
	s_nop 0
	s_nop 0
	s_nop 0
	s_nop 0
	s_nop 0
	s_nop 0
	s_nop 0
	s_nop 0
	s_nop 0
	s_lshl_b32 s0, s18, 5
	s_add_i32 s0, s17, s0
	s_ashr_i32 s1, s0, 31
	s_lshl_b64 s[0:1], s[0:1], 12
	s_add_u32 s0, s51, s0
	s_addc_u32 s1, s52, s1
	s_lshl_b32 s2, s16, 1
	s_waitcnt lgkmcnt(7)
	v_lshlrev_b32_e32 v218, 16, v153
	v_and_b32_e32 v219, 0xffff0000, v153
	s_add_u32 s2, s0, s2
	v_pk_fma_f32 v[218:219], v[66:67], v[14:15], v[218:219] op_sel_hi:[1,0,1] neg_lo:[1,0,0] neg_hi:[1,0,0]
	s_waitcnt lgkmcnt(0)
	v_lshlrev_b32_e32 v208, 16, v5
	v_and_b32_e32 v209, 0xffff0000, v5
	s_addc_u32 s3, s1, 0
	v_lshlrev_b32_e32 v0, 1, v178
	v_pk_fma_f32 v[30:31], v[30:31], v[14:15], v[208:209] op_sel_hi:[1,0,1] neg_lo:[1,0,0] neg_hi:[1,0,0]
	v_lshl_add_u64 v[208:209], s[2:3], 0, v[0:1]
	v_lshlrev_b32_e32 v0, 1, v180
	v_lshl_add_u64 v[208:209], v[208:209], 0, v[0:1]
	s_waitcnt vmcnt(15)
	v_pk_mul_f32 v[66:67], v[162:163], v[218:219]
	v_lshlrev_b32_e32 v162, 16, v152
	v_and_b32_e32 v163, 0xffff0000, v152
	v_pk_fma_f32 v[64:65], v[64:65], v[14:15], v[162:163] op_sel_hi:[1,0,1] neg_lo:[1,0,0] neg_hi:[1,0,0]
	s_waitcnt vmcnt(0)
	v_pk_mul_f32 v[12:13], v[30:31], v[12:13]
	v_mul_f32_e32 v0, v65, v65
	v_pk_fma_f32 v[152:153], v[64:65], v[64:65], v[0:1] op_sel_hi:[1,1,0]
	v_pk_mul_f32 v[64:65], v[160:161], v[64:65]
	v_lshlrev_b32_e32 v160, 16, v155
	v_and_b32_e32 v161, 0xffff0000, v155
	v_pk_fma_f32 v[160:161], v[70:71], v[14:15], v[160:161] op_sel_hi:[1,0,1] neg_lo:[1,0,0] neg_hi:[1,0,0]
	v_pk_fma_f32 v[152:153], v[218:219], v[218:219], v[152:153]
	v_mul_f32_e32 v0, v219, v219
	v_pk_mul_f32 v[70:71], v[160:161], v[158:159]
	v_lshlrev_b32_e32 v158, 16, v154
	v_and_b32_e32 v159, 0xffff0000, v154
	v_pk_add_f32 v[152:153], v[0:1], v[152:153] op_sel_hi:[0,1]
	v_pk_fma_f32 v[154:155], v[68:69], v[14:15], v[158:159] op_sel_hi:[1,0,1] neg_lo:[1,0,0] neg_hi:[1,0,0]
	s_nop 0
	v_pk_mul_f32 v[68:69], v[154:155], v[156:157]
	v_pk_fma_f32 v[152:153], v[154:155], v[154:155], v[152:153]
	v_mul_f32_e32 v0, v155, v155
	v_lshlrev_b32_e32 v154, 16, v133
	v_and_b32_e32 v155, 0xffff0000, v133
	v_pk_add_f32 v[152:153], v[0:1], v[152:153] op_sel_hi:[0,1]
	v_pk_fma_f32 v[154:155], v[74:75], v[14:15], v[154:155] op_sel_hi:[1,0,1] neg_lo:[1,0,0] neg_hi:[1,0,0]
	v_pk_fma_f32 v[152:153], v[160:161], v[160:161], v[152:153]
	v_mul_f32_e32 v0, v161, v161
	v_pk_mul_f32 v[74:75], v[154:155], v[150:151]
	v_lshlrev_b32_e32 v150, 16, v132
	v_and_b32_e32 v151, 0xffff0000, v132
	v_pk_add_f32 v[152:153], v[0:1], v[152:153] op_sel_hi:[0,1]
	v_pk_fma_f32 v[132:133], v[72:73], v[14:15], v[150:151] op_sel_hi:[1,0,1] neg_lo:[1,0,0] neg_hi:[1,0,0]
	s_nop 0
	v_pk_mul_f32 v[72:73], v[132:133], v[148:149]
	v_pk_fma_f32 v[148:149], v[132:133], v[132:133], v[152:153]
	v_mul_f32_e32 v0, v133, v133
	v_pk_add_f32 v[132:133], v[0:1], v[148:149] op_sel_hi:[0,1]
	v_lshlrev_b32_e32 v148, 16, v135
	v_and_b32_e32 v149, 0xffff0000, v135
	v_pk_fma_f32 v[148:149], v[78:79], v[14:15], v[148:149] op_sel_hi:[1,0,1] neg_lo:[1,0,0] neg_hi:[1,0,0]
	v_pk_fma_f32 v[132:133], v[154:155], v[154:155], v[132:133]
	v_mul_f32_e32 v0, v155, v155
	v_pk_mul_f32 v[78:79], v[148:149], v[146:147]
	v_lshlrev_b32_e32 v146, 16, v134
	v_and_b32_e32 v147, 0xffff0000, v134
	v_pk_add_f32 v[132:133], v[0:1], v[132:133] op_sel_hi:[0,1]
	v_pk_fma_f32 v[134:135], v[76:77], v[14:15], v[146:147] op_sel_hi:[1,0,1] neg_lo:[1,0,0] neg_hi:[1,0,0]
	s_nop 0
	v_pk_mul_f32 v[76:77], v[134:135], v[144:145]
	v_pk_fma_f32 v[132:133], v[134:135], v[134:135], v[132:133]
	v_mul_f32_e32 v0, v135, v135
	v_lshlrev_b32_e32 v134, 16, v121
	v_and_b32_e32 v135, 0xffff0000, v121
	v_pk_add_f32 v[132:133], v[0:1], v[132:133] op_sel_hi:[0,1]
	v_pk_fma_f32 v[134:135], v[50:51], v[14:15], v[134:135] op_sel_hi:[1,0,1] neg_lo:[1,0,0] neg_hi:[1,0,0]
	v_pk_fma_f32 v[132:133], v[148:149], v[148:149], v[132:133]
	v_mul_f32_e32 v0, v149, v149
	v_pk_mul_f32 v[50:51], v[134:135], v[142:143]
	v_lshlrev_b32_e32 v142, 16, v120
	v_and_b32_e32 v143, 0xffff0000, v120
	v_pk_add_f32 v[132:133], v[0:1], v[132:133] op_sel_hi:[0,1]
	v_pk_fma_f32 v[120:121], v[48:49], v[14:15], v[142:143] op_sel_hi:[1,0,1] neg_lo:[1,0,0] neg_hi:[1,0,0]
	s_nop 0
	v_pk_fma_f32 v[132:133], v[120:121], v[120:121], v[132:133]
	v_mul_f32_e32 v0, v121, v121
	v_pk_mul_f32 v[48:49], v[120:121], v[140:141]
	v_pk_add_f32 v[120:121], v[0:1], v[132:133] op_sel_hi:[0,1]
	v_pk_fma_f32 v[120:121], v[134:135], v[134:135], v[120:121]
	v_mul_f32_e32 v0, v135, v135
	v_lshlrev_b32_e32 v134, 16, v122
	v_and_b32_e32 v135, 0xffff0000, v122
	v_pk_add_f32 v[120:121], v[0:1], v[120:121] op_sel_hi:[0,1]
	v_lshlrev_b32_e32 v132, 16, v123
	v_and_b32_e32 v133, 0xffff0000, v123
	v_pk_fma_f32 v[122:123], v[52:53], v[14:15], v[134:135] op_sel_hi:[1,0,1] neg_lo:[1,0,0] neg_hi:[1,0,0]
	v_pk_fma_f32 v[132:133], v[54:55], v[14:15], v[132:133] op_sel_hi:[1,0,1] neg_lo:[1,0,0] neg_hi:[1,0,0]
	v_pk_mul_f32 v[52:53], v[122:123], v[136:137]
	v_pk_fma_f32 v[120:121], v[122:123], v[122:123], v[120:121]
	v_mul_f32_e32 v0, v123, v123
	v_lshlrev_b32_e32 v122, 16, v109
	v_and_b32_e32 v123, 0xffff0000, v109
	v_pk_add_f32 v[120:121], v[0:1], v[120:121] op_sel_hi:[0,1]
	v_pk_fma_f32 v[122:123], v[58:59], v[14:15], v[122:123] op_sel_hi:[1,0,1] neg_lo:[1,0,0] neg_hi:[1,0,0]
	v_pk_fma_f32 v[120:121], v[132:133], v[132:133], v[120:121]
	v_mul_f32_e32 v0, v133, v133
	v_pk_mul_f32 v[58:59], v[122:123], v[130:131]
	v_lshlrev_b32_e32 v130, 16, v108
	v_and_b32_e32 v131, 0xffff0000, v108
	v_pk_add_f32 v[120:121], v[0:1], v[120:121] op_sel_hi:[0,1]
	v_pk_fma_f32 v[108:109], v[56:57], v[14:15], v[130:131] op_sel_hi:[1,0,1] neg_lo:[1,0,0] neg_hi:[1,0,0]
	v_pk_mul_f32 v[54:55], v[132:133], v[138:139]
	v_pk_fma_f32 v[120:121], v[108:109], v[108:109], v[120:121]
	v_mul_f32_e32 v0, v109, v109
	v_pk_mul_f32 v[56:57], v[108:109], v[128:129]
	v_pk_add_f32 v[108:109], v[0:1], v[120:121] op_sel_hi:[0,1]
	v_pk_fma_f32 v[108:109], v[122:123], v[122:123], v[108:109]
	v_mul_f32_e32 v0, v123, v123
	v_lshlrev_b32_e32 v122, 16, v110
	v_and_b32_e32 v123, 0xffff0000, v110
	v_pk_add_f32 v[108:109], v[0:1], v[108:109] op_sel_hi:[0,1]
	v_lshlrev_b32_e32 v120, 16, v111
	v_and_b32_e32 v121, 0xffff0000, v111
	v_pk_fma_f32 v[110:111], v[60:61], v[14:15], v[122:123] op_sel_hi:[1,0,1] neg_lo:[1,0,0] neg_hi:[1,0,0]
	v_pk_fma_f32 v[120:121], v[62:63], v[14:15], v[120:121] op_sel_hi:[1,0,1] neg_lo:[1,0,0] neg_hi:[1,0,0]
	v_pk_mul_f32 v[60:61], v[110:111], v[124:125]
	v_pk_fma_f32 v[108:109], v[110:111], v[110:111], v[108:109]
	v_mul_f32_e32 v0, v111, v111
	v_lshlrev_b32_e32 v110, 16, v97
	v_and_b32_e32 v111, 0xffff0000, v97
	v_pk_add_f32 v[108:109], v[0:1], v[108:109] op_sel_hi:[0,1]
	v_pk_fma_f32 v[110:111], v[34:35], v[14:15], v[110:111] op_sel_hi:[1,0,1] neg_lo:[1,0,0] neg_hi:[1,0,0]
	v_pk_fma_f32 v[108:109], v[120:121], v[120:121], v[108:109]
	v_mul_f32_e32 v0, v121, v121
	v_pk_mul_f32 v[34:35], v[110:111], v[118:119]
	v_lshlrev_b32_e32 v118, 16, v96
	v_and_b32_e32 v119, 0xffff0000, v96
	v_pk_add_f32 v[108:109], v[0:1], v[108:109] op_sel_hi:[0,1]
	v_pk_fma_f32 v[96:97], v[32:33], v[14:15], v[118:119] op_sel_hi:[1,0,1] neg_lo:[1,0,0] neg_hi:[1,0,0]
	v_pk_mul_f32 v[62:63], v[120:121], v[126:127]
	v_pk_fma_f32 v[108:109], v[96:97], v[96:97], v[108:109]
	v_mul_f32_e32 v0, v97, v97
	v_pk_mul_f32 v[32:33], v[96:97], v[116:117]
	v_pk_add_f32 v[96:97], v[0:1], v[108:109] op_sel_hi:[0,1]
	v_pk_fma_f32 v[96:97], v[110:111], v[110:111], v[96:97]
	v_mul_f32_e32 v0, v111, v111
	v_lshlrev_b32_e32 v110, 16, v98
	v_and_b32_e32 v111, 0xffff0000, v98
	v_pk_add_f32 v[96:97], v[0:1], v[96:97] op_sel_hi:[0,1]
	v_pk_fma_f32 v[36:37], v[36:37], v[14:15], v[110:111] op_sel_hi:[1,0,1] neg_lo:[1,0,0] neg_hi:[1,0,0]
	v_lshlrev_b32_e32 v108, 16, v99
	v_pk_fma_f32 v[96:97], v[36:37], v[36:37], v[96:97]
	v_mul_f32_e32 v0, v37, v37
	v_and_b32_e32 v109, 0xffff0000, v99
	v_pk_mul_f32 v[98:99], v[36:37], v[112:113]
	v_pk_add_f32 v[36:37], v[0:1], v[96:97] op_sel_hi:[0,1]
	v_lshlrev_b32_e32 v96, 16, v85
	v_and_b32_e32 v97, 0xffff0000, v85
	v_pk_fma_f32 v[108:109], v[38:39], v[14:15], v[108:109] op_sel_hi:[1,0,1] neg_lo:[1,0,0] neg_hi:[1,0,0]
	v_pk_fma_f32 v[42:43], v[42:43], v[14:15], v[96:97] op_sel_hi:[1,0,1] neg_lo:[1,0,0] neg_hi:[1,0,0]
	v_pk_fma_f32 v[36:37], v[108:109], v[108:109], v[36:37]
	v_mul_f32_e32 v0, v109, v109
	v_pk_mul_f32 v[96:97], v[42:43], v[106:107]
	v_lshlrev_b32_e32 v106, 16, v84
	v_and_b32_e32 v107, 0xffff0000, v84
	v_pk_add_f32 v[36:37], v[0:1], v[36:37] op_sel_hi:[0,1]
	v_pk_fma_f32 v[40:41], v[40:41], v[14:15], v[106:107] op_sel_hi:[1,0,1] neg_lo:[1,0,0] neg_hi:[1,0,0]
	v_pk_mul_f32 v[38:39], v[108:109], v[114:115]
	v_pk_fma_f32 v[36:37], v[40:41], v[40:41], v[36:37]
	v_mul_f32_e32 v0, v41, v41
	v_pk_mul_f32 v[84:85], v[40:41], v[104:105]
	v_pk_add_f32 v[36:37], v[0:1], v[36:37] op_sel_hi:[0,1]
	v_lshlrev_b32_e32 v40, 16, v87
	v_and_b32_e32 v41, 0xffff0000, v87
	v_pk_fma_f32 v[36:37], v[42:43], v[42:43], v[36:37]
	v_mul_f32_e32 v0, v43, v43
	v_pk_fma_f32 v[40:41], v[46:47], v[14:15], v[40:41] op_sel_hi:[1,0,1] neg_lo:[1,0,0] neg_hi:[1,0,0]
	v_lshlrev_b32_e32 v46, 16, v86
	v_and_b32_e32 v47, 0xffff0000, v86
	v_pk_add_f32 v[36:37], v[0:1], v[36:37] op_sel_hi:[0,1]
	v_pk_fma_f32 v[44:45], v[44:45], v[14:15], v[46:47] op_sel_hi:[1,0,1] neg_lo:[1,0,0] neg_hi:[1,0,0]
	v_pk_mul_f32 v[42:43], v[40:41], v[102:103]
	v_pk_fma_f32 v[36:37], v[44:45], v[44:45], v[36:37]
	v_mul_f32_e32 v0, v45, v45
	v_pk_add_f32 v[36:37], v[0:1], v[36:37] op_sel_hi:[0,1]
	v_pk_mul_f32 v[46:47], v[44:45], v[100:101]
	v_pk_fma_f32 v[36:37], v[40:41], v[40:41], v[36:37]
	v_mul_f32_e32 v0, v41, v41
	v_lshlrev_b32_e32 v44, 16, v6
	v_and_b32_e32 v45, 0xffff0000, v6
	v_pk_add_f32 v[36:37], v[0:1], v[36:37] op_sel_hi:[0,1]
	v_lshlrev_b32_e32 v40, 16, v7
	v_and_b32_e32 v41, 0xffff0000, v7
	v_pk_fma_f32 v[6:7], v[16:17], v[14:15], v[44:45] op_sel_hi:[1,0,1] neg_lo:[1,0,0] neg_hi:[1,0,0]
	v_pk_fma_f32 v[18:19], v[18:19], v[14:15], v[40:41] op_sel_hi:[1,0,1] neg_lo:[1,0,0] neg_hi:[1,0,0]
	v_pk_fma_f32 v[36:37], v[6:7], v[6:7], v[36:37]
	v_mul_f32_e32 v0, v7, v7
	v_pk_mul_f32 v[16:17], v[6:7], v[92:93]
	v_pk_add_f32 v[6:7], v[0:1], v[36:37] op_sel_hi:[0,1]
	v_pk_fma_f32 v[6:7], v[18:19], v[18:19], v[6:7]
	v_mul_f32_e32 v0, v19, v19
	v_lshlrev_b32_e32 v36, 16, v8
	v_and_b32_e32 v37, 0xffff0000, v8
	v_pk_mul_f32 v[40:41], v[18:19], v[94:95]
	v_pk_add_f32 v[6:7], v[0:1], v[6:7] op_sel_hi:[0,1]
	v_lshlrev_b32_e32 v18, 16, v9
	v_and_b32_e32 v19, 0xffff0000, v9
	v_pk_fma_f32 v[8:9], v[20:21], v[14:15], v[36:37] op_sel_hi:[1,0,1] neg_lo:[1,0,0] neg_hi:[1,0,0]
	v_pk_fma_f32 v[18:19], v[22:23], v[14:15], v[18:19] op_sel_hi:[1,0,1] neg_lo:[1,0,0] neg_hi:[1,0,0]
	v_pk_fma_f32 v[6:7], v[8:9], v[8:9], v[6:7]
	v_mul_f32_e32 v0, v9, v9
	v_pk_mul_f32 v[20:21], v[8:9], v[88:89]
	v_pk_add_f32 v[6:7], v[0:1], v[6:7] op_sel_hi:[0,1]
	v_lshlrev_b32_e32 v8, 16, v3
	v_and_b32_e32 v9, 0xffff0000, v3
	v_pk_fma_f32 v[6:7], v[18:19], v[18:19], v[6:7]
	v_mul_f32_e32 v0, v19, v19
	v_pk_fma_f32 v[8:9], v[26:27], v[14:15], v[8:9] op_sel_hi:[1,0,1] neg_lo:[1,0,0] neg_hi:[1,0,0]
	v_lshlrev_b32_e32 v26, 16, v2
	v_and_b32_e32 v27, 0xffff0000, v2
	v_pk_add_f32 v[6:7], v[0:1], v[6:7] op_sel_hi:[0,1]
	v_pk_fma_f32 v[2:3], v[24:25], v[14:15], v[26:27] op_sel_hi:[1,0,1] neg_lo:[1,0,0] neg_hi:[1,0,0]
	v_pk_mul_f32 v[22:23], v[18:19], v[90:91]
	v_pk_fma_f32 v[6:7], v[2:3], v[2:3], v[6:7]
	v_mul_f32_e32 v0, v3, v3
	v_pk_mul_f32 v[24:25], v[2:3], v[80:81]
	v_pk_add_f32 v[2:3], v[0:1], v[6:7] op_sel_hi:[0,1]
	v_pk_fma_f32 v[2:3], v[8:9], v[8:9], v[2:3]
	v_mul_f32_e32 v0, v9, v9
	v_lshlrev_b32_e32 v6, 16, v4
	v_and_b32_e32 v7, 0xffff0000, v4
	v_pk_add_f32 v[2:3], v[0:1], v[2:3] op_sel_hi:[0,1]
	v_pk_fma_f32 v[4:5], v[28:29], v[14:15], v[6:7] op_sel_hi:[1,0,1] neg_lo:[1,0,0] neg_hi:[1,0,0]
	v_pk_mul_f32 v[18:19], v[8:9], v[82:83]
	v_pk_fma_f32 v[2:3], v[4:5], v[4:5], v[2:3]
	v_mul_f32_e32 v0, v5, v5
	v_pk_add_f32 v[2:3], v[0:1], v[2:3] op_sel_hi:[0,1]
	v_pk_fma_f32 v[2:3], v[30:31], v[30:31], v[2:3]
	v_mul_f32_e32 v0, v31, v31
	v_pk_add_f32 v[2:3], v[0:1], v[2:3] op_sel_hi:[0,1]
	v_mov_b32_e32 v0, v2
	s_nop 1
	v_permlane32_swap_b32_e32 v2, v0
	v_add_f32_e32 v0, v2, v0
	v_fmamk_f32 v0, v0, 0x3c000000, v233
	v_rsq_f32_e32 v0, v0
	v_pk_mul_f32 v[6:7], v[4:5], v[10:11]
	v_mul_f32_e32 v0, v216, v0
	v_pk_mul_f32 v[2:3], v[64:65], v[0:1] op_sel_hi:[1,0]
	v_pk_mul_f32 v[4:5], v[66:67], v[0:1] op_sel_hi:[1,0]
	v_cvt_pk_bf16_f32 v2, v2, v3
	v_cvt_pk_bf16_f32 v3, v4, v5
	global_store_dwordx2 v[208:209], v[2:3], off
	v_pk_mul_f32 v[2:3], v[68:69], v[0:1] op_sel_hi:[1,0]
	v_pk_mul_f32 v[4:5], v[70:71], v[0:1] op_sel_hi:[1,0]
	v_cvt_pk_bf16_f32 v2, v2, v3
	v_cvt_pk_bf16_f32 v3, v4, v5
	global_store_dwordx2 v[208:209], v[2:3], off offset:16
	v_pk_mul_f32 v[2:3], v[72:73], v[0:1] op_sel_hi:[1,0]
	v_pk_mul_f32 v[4:5], v[74:75], v[0:1] op_sel_hi:[1,0]
	v_cvt_pk_bf16_f32 v2, v2, v3
	v_cvt_pk_bf16_f32 v3, v4, v5
	global_store_dwordx2 v[208:209], v[2:3], off offset:32
	v_pk_mul_f32 v[2:3], v[76:77], v[0:1] op_sel_hi:[1,0]
	v_pk_mul_f32 v[4:5], v[78:79], v[0:1] op_sel_hi:[1,0]
	v_cvt_pk_bf16_f32 v2, v2, v3
	v_cvt_pk_bf16_f32 v3, v4, v5
	global_store_dwordx2 v[208:209], v[2:3], off offset:48
	v_pk_mul_f32 v[2:3], v[48:49], v[0:1] op_sel_hi:[1,0]
	v_pk_mul_f32 v[4:5], v[50:51], v[0:1] op_sel_hi:[1,0]
	v_cvt_pk_bf16_f32 v2, v2, v3
	v_cvt_pk_bf16_f32 v3, v4, v5
	global_store_dwordx2 v[208:209], v[2:3], off offset:64
	v_pk_mul_f32 v[2:3], v[52:53], v[0:1] op_sel_hi:[1,0]
	v_pk_mul_f32 v[4:5], v[54:55], v[0:1] op_sel_hi:[1,0]
	v_cvt_pk_bf16_f32 v2, v2, v3
	v_cvt_pk_bf16_f32 v3, v4, v5
	global_store_dwordx2 v[208:209], v[2:3], off offset:80
	v_pk_mul_f32 v[2:3], v[56:57], v[0:1] op_sel_hi:[1,0]
	v_pk_mul_f32 v[4:5], v[58:59], v[0:1] op_sel_hi:[1,0]
	v_cvt_pk_bf16_f32 v2, v2, v3
	v_cvt_pk_bf16_f32 v3, v4, v5
	global_store_dwordx2 v[208:209], v[2:3], off offset:96
	v_pk_mul_f32 v[2:3], v[60:61], v[0:1] op_sel_hi:[1,0]
	v_pk_mul_f32 v[4:5], v[62:63], v[0:1] op_sel_hi:[1,0]
	v_cvt_pk_bf16_f32 v2, v2, v3
	v_cvt_pk_bf16_f32 v3, v4, v5
	global_store_dwordx2 v[208:209], v[2:3], off offset:112
	v_pk_mul_f32 v[2:3], v[32:33], v[0:1] op_sel_hi:[1,0]
	v_pk_mul_f32 v[4:5], v[34:35], v[0:1] op_sel_hi:[1,0]
	v_cvt_pk_bf16_f32 v2, v2, v3
	v_cvt_pk_bf16_f32 v3, v4, v5
	global_store_dwordx2 v[208:209], v[2:3], off offset:128
	v_pk_mul_f32 v[2:3], v[98:99], v[0:1] op_sel_hi:[1,0]
	v_pk_mul_f32 v[4:5], v[38:39], v[0:1] op_sel_hi:[1,0]
	v_cvt_pk_bf16_f32 v2, v2, v3
	v_cvt_pk_bf16_f32 v3, v4, v5
	global_store_dwordx2 v[208:209], v[2:3], off offset:144
	v_pk_mul_f32 v[2:3], v[84:85], v[0:1] op_sel_hi:[1,0]
	v_pk_mul_f32 v[4:5], v[96:97], v[0:1] op_sel_hi:[1,0]
	v_cvt_pk_bf16_f32 v2, v2, v3
	v_cvt_pk_bf16_f32 v3, v4, v5
	global_store_dwordx2 v[208:209], v[2:3], off offset:160
	v_pk_mul_f32 v[2:3], v[46:47], v[0:1] op_sel_hi:[1,0]
	v_pk_mul_f32 v[4:5], v[42:43], v[0:1] op_sel_hi:[1,0]
	v_cvt_pk_bf16_f32 v2, v2, v3
	v_cvt_pk_bf16_f32 v3, v4, v5
	global_store_dwordx2 v[208:209], v[2:3], off offset:176
	v_pk_mul_f32 v[2:3], v[16:17], v[0:1] op_sel_hi:[1,0]
	v_pk_mul_f32 v[4:5], v[40:41], v[0:1] op_sel_hi:[1,0]
	v_cvt_pk_bf16_f32 v2, v2, v3
	v_cvt_pk_bf16_f32 v3, v4, v5
	global_store_dwordx2 v[208:209], v[2:3], off offset:192
	v_pk_mul_f32 v[2:3], v[20:21], v[0:1] op_sel_hi:[1,0]
	v_pk_mul_f32 v[4:5], v[22:23], v[0:1] op_sel_hi:[1,0]
	v_cvt_pk_bf16_f32 v2, v2, v3
	v_cvt_pk_bf16_f32 v3, v4, v5
	global_store_dwordx2 v[208:209], v[2:3], off offset:208
	v_pk_mul_f32 v[2:3], v[24:25], v[0:1] op_sel_hi:[1,0]
	v_pk_mul_f32 v[4:5], v[18:19], v[0:1] op_sel_hi:[1,0]
	v_cvt_pk_bf16_f32 v2, v2, v3
	v_cvt_pk_bf16_f32 v3, v4, v5
	global_store_dwordx2 v[208:209], v[2:3], off offset:224
	v_pk_mul_f32 v[2:3], v[6:7], v[0:1] op_sel_hi:[1,0]
	v_pk_mul_f32 v[4:5], v[12:13], v[0:1] op_sel_hi:[1,0]
	v_cvt_pk_bf16_f32 v2, v2, v3
	s_cbranch_execz .LBB0_716
	s_branch .LBB0_816

.LBB0_1229:
	global_load_dwordx4 v[0:3], v[44:45], off
	global_load_dwordx4 v[4:7], v[44:45], off offset:16
	s_nop 0
	v_pk_mul_f32 v[8:9], v[84:85], v[84:85]
	v_pk_mul_f32 v[10:11], v[86:87], v[86:87]
	v_add_f32_e32 v8, v9, v8
	v_add_f32_e32 v8, v10, v8
	v_pk_mul_f32 v[12:13], v[80:81], v[80:81]
	v_add_f32_e32 v8, v11, v8
	v_add_f32_e32 v8, v12, v8
	v_pk_mul_f32 v[14:15], v[82:83], v[82:83]
	v_add_f32_e32 v8, v13, v8
	v_add_f32_e32 v8, v14, v8
	v_pk_mul_f32 v[16:17], v[76:77], v[76:77]
	v_add_f32_e32 v8, v15, v8
	v_add_f32_e32 v8, v16, v8
	v_pk_mul_f32 v[18:19], v[78:79], v[78:79]
	v_add_f32_e32 v8, v17, v8
	v_add_f32_e32 v8, v18, v8
	v_pk_mul_f32 v[20:21], v[72:73], v[72:73]
	v_add_f32_e32 v8, v19, v8
	v_add_f32_e32 v8, v20, v8
	v_pk_mul_f32 v[22:23], v[74:75], v[74:75]
	v_add_f32_e32 v8, v21, v8
	v_add_f32_e32 v8, v22, v8
	v_pk_mul_f32 v[24:25], v[68:69], v[68:69]
	v_add_f32_e32 v8, v23, v8
	v_add_f32_e32 v8, v24, v8
	v_pk_mul_f32 v[26:27], v[70:71], v[70:71]
	v_add_f32_e32 v8, v25, v8
	v_add_f32_e32 v8, v26, v8
	v_pk_mul_f32 v[28:29], v[64:65], v[64:65]
	v_add_f32_e32 v8, v27, v8
	v_add_f32_e32 v8, v28, v8
	v_pk_mul_f32 v[30:31], v[66:67], v[66:67]
	v_add_f32_e32 v8, v29, v8
	v_add_f32_e32 v8, v30, v8
	v_pk_mul_f32 v[32:33], v[56:57], v[56:57]
	v_add_f32_e32 v8, v31, v8
	v_add_f32_e32 v8, v32, v8
	v_pk_mul_f32 v[34:35], v[60:61], v[60:61]
	v_add_f32_e32 v8, v33, v8
	v_add_f32_e32 v8, v34, v8
	v_pk_mul_f32 v[36:37], v[58:59], v[58:59]
	v_add_f32_e32 v8, v35, v8
	v_add_f32_e32 v8, v36, v8
	v_pk_mul_f32 v[38:39], v[62:63], v[62:63]
	v_add_f32_e32 v8, v37, v8
	v_add_f32_e32 v8, v38, v8
	v_add_f32_e32 v8, v39, v8
	s_add_i32 s2, s2, s82
	v_lshl_add_u64 v[52:53], v[52:53], 0, s[56:57]
	v_add_f32_dpp v8, v8, v8 quad_perm:[1,0,3,2] row_mask:0xf bank_mask:0xf bound_ctrl:1
	s_cmpk_lt_i32 s2, 0x2800
	s_nop 0
	v_add_f32_dpp v8, v8, v8 quad_perm:[2,3,0,1] row_mask:0xf bank_mask:0xf bound_ctrl:1
	s_nop 1
	v_add_f32_dpp v8, v8, v8 row_half_mirror row_mask:0xf bank_mask:0xf bound_ctrl:1
	s_nop 1
	v_add_f32_dpp v8, v8, v8 row_mirror row_mask:0xf bank_mask:0xf bound_ctrl:1
	ds_swizzle_b32 v9, v8 offset:swizzle(SWAP,16)
	s_waitcnt lgkmcnt(0)
	v_add_f32_e32 v8, v8, v9
	v_mov_b32_e32 v9, v8
	s_nop 1
	v_permlane32_swap_b32_e32 v8, v9
	v_add_f32_e32 v8, v8, v9
	v_fmamk_f32 v8, v8, 0x3a000000, v99
	v_rsq_f32_e32 v8, v8
	s_nop 0
	v_pk_mul_f32 v[10:11], v[84:85], v[8:9] op_sel_hi:[1,0]
	v_pk_mul_f32 v[12:13], v[86:87], v[8:9] op_sel_hi:[1,0]
	v_pk_mul_f32 v[14:15], v[80:81], v[8:9] op_sel_hi:[1,0]
	v_pk_mul_f32 v[16:17], v[82:83], v[8:9] op_sel_hi:[1,0]
	s_waitcnt vmcnt(2)
	s_waitcnt vmcnt(1)
	v_pk_mul_f32 v[2:3], v[2:3], v[12:13]
	v_pk_mul_f32 v[0:1], v[0:1], v[10:11]
	s_waitcnt vmcnt(0)
	v_pk_mul_f32 v[6:7], v[6:7], v[16:17]
	v_pk_mul_f32 v[4:5], v[4:5], v[14:15]
	global_store_dwordx4 v[54:55], v[0:3], off offset:-4096
	global_store_dwordx4 v[54:55], v[4:7], off offset:-4080
	global_load_dwordx4 v[0:3], v[44:45], off offset:2048
	global_load_dwordx4 v[4:7], v[44:45], off offset:2064
	s_nop 0
	s_nop 0
	v_pk_mul_f32 v[10:11], v[78:79], v[8:9] op_sel_hi:[1,0]
	v_pk_mul_f32 v[12:13], v[76:77], v[8:9] op_sel_hi:[1,0]
	v_pk_mul_f32 v[14:15], v[74:75], v[8:9] op_sel_hi:[1,0]
	v_pk_mul_f32 v[16:17], v[72:73], v[8:9] op_sel_hi:[1,0]
	s_waitcnt vmcnt(1)
	v_pk_mul_f32 v[0:1], v[0:1], v[12:13]
	v_pk_mul_f32 v[2:3], v[2:3], v[10:11]
	s_waitcnt vmcnt(0)
	v_pk_mul_f32 v[4:5], v[4:5], v[16:17]
	v_pk_mul_f32 v[6:7], v[6:7], v[14:15]
	global_store_dwordx4 v[54:55], v[0:3], off offset:-2048
	global_store_dwordx4 v[54:55], v[4:7], off offset:-2032
	global_load_dwordx4 v[0:3], v[46:47], off
	global_load_dwordx4 v[4:7], v[46:47], off offset:16
	s_nop 0
	s_nop 0
	v_pk_mul_f32 v[10:11], v[70:71], v[8:9] op_sel_hi:[1,0]
	v_pk_mul_f32 v[12:13], v[68:69], v[8:9] op_sel_hi:[1,0]
	v_pk_mul_f32 v[14:15], v[66:67], v[8:9] op_sel_hi:[1,0]
	v_pk_mul_f32 v[16:17], v[64:65], v[8:9] op_sel_hi:[1,0]
	s_waitcnt vmcnt(1)
	v_pk_mul_f32 v[0:1], v[12:13], v[0:1]
	v_pk_mul_f32 v[2:3], v[10:11], v[2:3]
	s_waitcnt vmcnt(0)
	v_pk_mul_f32 v[4:5], v[16:17], v[4:5]
	v_pk_mul_f32 v[6:7], v[14:15], v[6:7]
	global_store_dwordx4 v[54:55], v[0:3], off
	global_store_dwordx4 v[54:55], v[4:7], off offset:16
	global_load_dwordx4 v[0:3], v[48:49], off
	global_load_dwordx4 v[4:7], v[48:49], off offset:16
	s_nop 0
	s_nop 0
	v_pk_mul_f32 v[10:11], v[60:61], v[8:9] op_sel_hi:[1,0]
	v_pk_mul_f32 v[12:13], v[56:57], v[8:9] op_sel_hi:[1,0]
	v_pk_mul_f32 v[14:15], v[62:63], v[8:9] op_sel_hi:[1,0]
	v_pk_mul_f32 v[8:9], v[58:59], v[8:9] op_sel_hi:[1,0]
	s_waitcnt vmcnt(1)
	v_pk_mul_f32 v[0:1], v[12:13], v[0:1]
	v_pk_mul_f32 v[2:3], v[10:11], v[2:3]
	s_waitcnt vmcnt(0)
	v_pk_mul_f32 v[4:5], v[8:9], v[4:5]
	v_pk_mul_f32 v[6:7], v[14:15], v[6:7]
	global_store_dwordx4 v[54:55], v[0:3], off offset:2048
	global_store_dwordx4 v[54:55], v[4:7], off offset:2064
	v_lshl_add_u64 v[54:55], v[54:55], 0, s[4:5]
	s_cbranch_scc0 .LBB0_1232
.LBB0_1230:
	global_load_dwordx4 v[0:3], v[52:53], off
	global_load_dwordx4 v[4:7], v[52:53], off offset:1024
	global_load_dwordx4 v[8:11], v[52:53], off offset:2048
	global_load_dwordx4 v[12:15], v[52:53], off offset:3072
	s_cmpk_lt_i32 s2, 0x2000
	s_waitcnt vmcnt(0)
	v_and_b32_e32 v85, 0xffff0000, v0
	v_lshlrev_b32_e32 v84, 16, v0
	v_and_b32_e32 v87, 0xffff0000, v1
	v_lshlrev_b32_e32 v86, 16, v1
	v_and_b32_e32 v81, 0xffff0000, v2
	v_lshlrev_b32_e32 v80, 16, v2
	v_and_b32_e32 v83, 0xffff0000, v3
	v_lshlrev_b32_e32 v82, 16, v3
	v_lshlrev_b32_e32 v76, 16, v4
	v_and_b32_e32 v77, 0xffff0000, v4
	v_lshlrev_b32_e32 v78, 16, v5
	v_and_b32_e32 v79, 0xffff0000, v5
	v_lshlrev_b32_e32 v72, 16, v6
	v_and_b32_e32 v73, 0xffff0000, v6
	v_lshlrev_b32_e32 v74, 16, v7
	v_and_b32_e32 v75, 0xffff0000, v7
	v_lshlrev_b32_e32 v68, 16, v8
	v_and_b32_e32 v69, 0xffff0000, v8
	v_lshlrev_b32_e32 v70, 16, v9
	v_and_b32_e32 v71, 0xffff0000, v9
	v_lshlrev_b32_e32 v64, 16, v10
	v_and_b32_e32 v65, 0xffff0000, v10
	v_lshlrev_b32_e32 v66, 16, v11
	v_and_b32_e32 v67, 0xffff0000, v11
	v_lshlrev_b32_e32 v56, 16, v12
	v_and_b32_e32 v57, 0xffff0000, v12
	v_lshlrev_b32_e32 v60, 16, v13
	v_and_b32_e32 v61, 0xffff0000, v13
	v_lshlrev_b32_e32 v58, 16, v14
	v_and_b32_e32 v59, 0xffff0000, v14
	v_lshlrev_b32_e32 v62, 16, v15
	v_and_b32_e32 v63, 0xffff0000, v15
	s_cbranch_scc1 .LBB0_1229
	s_add_i32 s0, s2, 0xffffe000
	s_lshl_b64 s[6:7], s[0:1], 12
	v_lshl_add_u64 v[88:89], v[50:51], 0, s[6:7]
	global_load_dwordx4 v[4:7], v[88:89], off
	global_load_dwordx4 v[0:3], v[88:89], off offset:1024
	v_add_co_u32_e32 v90, vcc, s3, v88
	s_nop 0
	s_nop 0
	v_addc_co_u32_e32 v91, vcc, 0, v89, vcc
	global_load_dwordx4 v[20:23], v[90:91], off
	v_add_co_u32_e32 v92, vcc, s10, v88
	s_nop 0
	s_nop 0
	v_addc_co_u32_e32 v93, vcc, 0, v89, vcc
	global_load_dwordx4 v[8:11], v[92:93], off
	v_add_co_u32_e32 v94, vcc, s11, v88
	s_nop 0
	s_nop 0
	v_addc_co_u32_e32 v95, vcc, 0, v89, vcc
	global_load_dwordx4 v[100:103], v[94:95], off
	s_lshr_b32 s0, s0, 10
	s_add_i32 s0, s0, 1
	s_mul_hi_u32 s7, s0, 0xc000
	s_mul_i32 s0, s0, 0xc000
	s_add_u32 s6, s8, s0
	s_addc_u32 s7, s9, s7
	global_load_dwordx4 v[104:107], v96, s[6:7]
	global_load_dwordx4 v[108:111], v96, s[6:7] offset:16
	global_load_dwordx4 v[24:27], v[90:91], off offset:1024
	global_load_dwordx4 v[16:19], v[92:93], off offset:1024
	global_load_dwordx4 v[12:15], v[94:95], off offset:1024
	global_load_dwordx4 v[32:35], v96, s[6:7] offset:2048
	global_load_dwordx4 v[28:31], v[88:89], off offset:2048
	global_load_dwordx4 v[36:39], v[90:91], off offset:2048
	global_load_dwordx4 v[112:115], v96, s[6:7] offset:2064
	global_load_dwordx4 v[40:43], v[92:93], off offset:2048
	global_load_dwordx4 v[116:119], v97, s[6:7]
	global_load_dwordx4 v[120:123], v[94:95], off offset:2048
	global_load_dwordx4 v[136:139], v97, s[6:7] offset:16
	global_load_dwordx4 v[140:143], v[88:89], off offset:3072
	global_load_dwordx4 v[144:147], v[90:91], off offset:3072
	global_load_dwordx4 v[148:151], v[92:93], off offset:3072
	global_load_dwordx4 v[152:155], v98, s[6:7] offset:16
	global_load_dwordx4 v[156:159], v[94:95], off offset:3072
	global_load_dwordx4 v[160:163], v98, s[6:7]
	s_nop 0
	s_nop 0
	s_nop 0
	s_nop 0
	s_nop 0
	s_nop 0
	s_nop 0
	s_nop 0
	s_nop 0
	s_nop 0
	s_nop 0
	s_waitcnt vmcnt(24)
	s_waitcnt vmcnt(23)
	v_and_b32_e32 v125, 0xffff0000, v4
	v_lshlrev_b32_e32 v124, 16, v4
	v_and_b32_e32 v127, 0xffff0000, v5
	v_lshlrev_b32_e32 v126, 16, v5
	v_and_b32_e32 v5, 0xffff0000, v6
	v_lshlrev_b32_e32 v4, 16, v6
	v_and_b32_e32 v129, 0xffff0000, v7
	v_lshlrev_b32_e32 v128, 16, v7
	s_waitcnt vmcnt(21)
	v_and_b32_e32 v131, 0xffff0000, v20
	v_lshlrev_b32_e32 v130, 16, v20
	v_and_b32_e32 v133, 0xffff0000, v21
	v_lshlrev_b32_e32 v132, 16, v21
	v_and_b32_e32 v21, 0xffff0000, v22
	v_lshlrev_b32_e32 v20, 16, v22
	v_and_b32_e32 v135, 0xffff0000, v23
	v_lshlrev_b32_e32 v134, 16, v23
	v_pk_add_f32 v[22:23], v[124:125], v[130:131]
	v_pk_add_f32 v[124:125], v[126:127], v[132:133]
	s_waitcnt vmcnt(20)
	v_and_b32_e32 v127, 0xffff0000, v8
	v_lshlrev_b32_e32 v126, 16, v8
	v_and_b32_e32 v131, 0xffff0000, v9
	v_lshlrev_b32_e32 v130, 16, v9
	v_and_b32_e32 v9, 0xffff0000, v10
	v_lshlrev_b32_e32 v8, 16, v10
	v_and_b32_e32 v133, 0xffff0000, v11
	v_lshlrev_b32_e32 v132, 16, v11
	v_pk_add_f32 v[4:5], v[4:5], v[20:21]
	v_pk_add_f32 v[10:11], v[128:129], v[134:135]
	s_waitcnt vmcnt(19)
	v_and_b32_e32 v21, 0xffff0000, v100
	v_lshlrev_b32_e32 v20, 16, v100
	v_and_b32_e32 v129, 0xffff0000, v101
	v_lshlrev_b32_e32 v128, 16, v101
	v_and_b32_e32 v101, 0xffff0000, v102
	v_lshlrev_b32_e32 v100, 16, v102
	v_and_b32_e32 v135, 0xffff0000, v103
	v_lshlrev_b32_e32 v134, 16, v103
	v_pk_add_f32 v[8:9], v[8:9], v[100:101]
	v_pk_add_f32 v[100:101], v[132:133], v[134:135]
	v_pk_add_f32 v[4:5], v[4:5], v[8:9]
	v_lshlrev_b32_e32 v6, 16, v0
	v_and_b32_e32 v7, 0xffff0000, v0
	v_pk_add_f32 v[8:9], v[10:11], v[100:101]
	s_waitcnt vmcnt(17)
	v_pk_fma_f32 v[80:81], v[108:109], v[4:5], v[80:81]
	s_waitcnt vmcnt(16)
	v_lshlrev_b32_e32 v4, 16, v24
	v_and_b32_e32 v5, 0xffff0000, v24
	v_pk_fma_f32 v[82:83], v[110:111], v[8:9], v[82:83]
	s_waitcnt vmcnt(15)
	v_lshlrev_b32_e32 v8, 16, v16
	v_and_b32_e32 v9, 0xffff0000, v16
	v_pk_add_f32 v[4:5], v[6:7], v[4:5]
	s_waitcnt vmcnt(14)
	v_lshlrev_b32_e32 v6, 16, v12
	v_and_b32_e32 v7, 0xffff0000, v12
	v_pk_add_f32 v[6:7], v[8:9], v[6:7]
	v_lshlrev_b32_e32 v0, 16, v1
	v_and_b32_e32 v1, 0xffff0000, v1
	v_lshlrev_b32_e32 v8, 16, v25
	v_and_b32_e32 v9, 0xffff0000, v25
	v_lshlrev_b32_e32 v10, 16, v17
	v_and_b32_e32 v11, 0xffff0000, v17
	v_pk_add_f32 v[0:1], v[0:1], v[8:9]
	v_lshlrev_b32_e32 v8, 16, v13
	v_and_b32_e32 v9, 0xffff0000, v13
	v_pk_add_f32 v[12:13], v[10:11], v[8:9]
	v_lshlrev_b32_e32 v24, 16, v18
	v_pk_add_f32 v[0:1], v[0:1], v[12:13]
	v_lshlrev_b32_e32 v12, 16, v26
	s_waitcnt vmcnt(13)
	v_pk_fma_f32 v[78:79], v[34:35], v[0:1], v[78:79]
	v_lshlrev_b32_e32 v0, 16, v2
	v_and_b32_e32 v1, 0xffff0000, v2
	v_and_b32_e32 v13, 0xffff0000, v26
	v_and_b32_e32 v25, 0xffff0000, v18
	v_pk_add_f32 v[0:1], v[0:1], v[12:13]
	v_lshlrev_b32_e32 v12, 16, v14
	v_and_b32_e32 v13, 0xffff0000, v14
	v_pk_add_f32 v[12:13], v[24:25], v[12:13]
	v_pk_add_f32 v[4:5], v[4:5], v[6:7]
	v_lshlrev_b32_e32 v2, 16, v3
	v_and_b32_e32 v3, 0xffff0000, v3
	v_lshlrev_b32_e32 v16, 16, v27
	v_and_b32_e32 v17, 0xffff0000, v27
	v_lshlrev_b32_e32 v18, 16, v19
	v_and_b32_e32 v19, 0xffff0000, v19
	v_pk_add_f32 v[0:1], v[0:1], v[12:13]
	v_lshlrev_b32_e32 v12, 16, v15
	v_and_b32_e32 v13, 0xffff0000, v15
	v_pk_add_f32 v[20:21], v[126:127], v[20:21]
	v_pk_add_f32 v[102:103], v[130:131], v[128:129]
	v_pk_fma_f32 v[76:77], v[32:33], v[4:5], v[76:77]
	s_nop 0
	s_waitcnt vmcnt(10)
	v_pk_fma_f32 v[72:73], v[112:113], v[0:1], v[72:73]
	v_pk_add_f32 v[0:1], v[2:3], v[16:17]
	v_pk_add_f32 v[2:3], v[18:19], v[12:13]
	v_pk_add_f32 v[20:21], v[22:23], v[20:21]
	v_pk_add_f32 v[22:23], v[124:125], v[102:103]
	v_pk_add_f32 v[0:1], v[0:1], v[2:3]
	v_pk_fma_f32 v[84:85], v[104:105], v[20:21], v[84:85]
	v_pk_fma_f32 v[86:87], v[106:107], v[22:23], v[86:87]
	s_nop 0
	s_nop 0
	s_nop 0
	v_pk_fma_f32 v[74:75], v[114:115], v[0:1], v[74:75]
	s_nop 0
	s_nop 0
	v_lshlrev_b32_e32 v12, 16, v28
	s_nop 0
	v_and_b32_e32 v13, 0xffff0000, v28
	v_lshlrev_b32_e32 v14, 16, v36
	v_and_b32_e32 v15, 0xffff0000, v36
	s_waitcnt vmcnt(9)
	v_lshlrev_b32_e32 v16, 16, v40
	v_and_b32_e32 v17, 0xffff0000, v40
	v_pk_add_f32 v[12:13], v[12:13], v[14:15]
	s_waitcnt vmcnt(7)
	v_lshlrev_b32_e32 v14, 16, v120
	v_and_b32_e32 v15, 0xffff0000, v120
	v_pk_add_f32 v[14:15], v[16:17], v[14:15]
	v_lshlrev_b32_e32 v16, 16, v121
	v_pk_add_f32 v[12:13], v[12:13], v[14:15]
	v_lshlrev_b32_e32 v14, 16, v37
	v_pk_fma_f32 v[68:69], v[116:117], v[12:13], v[68:69]
	v_lshlrev_b32_e32 v12, 16, v29
	v_and_b32_e32 v13, 0xffff0000, v29
	v_and_b32_e32 v15, 0xffff0000, v37
	v_pk_add_f32 v[12:13], v[12:13], v[14:15]
	v_lshlrev_b32_e32 v14, 16, v41
	v_and_b32_e32 v15, 0xffff0000, v41
	v_and_b32_e32 v17, 0xffff0000, v121
	v_pk_add_f32 v[14:15], v[14:15], v[16:17]
	v_lshlrev_b32_e32 v24, 16, v42
	v_pk_add_f32 v[12:13], v[12:13], v[14:15]
	v_lshlrev_b32_e32 v14, 16, v38
	v_pk_fma_f32 v[70:71], v[118:119], v[12:13], v[70:71]
	v_lshlrev_b32_e32 v12, 16, v30
	v_and_b32_e32 v13, 0xffff0000, v30
	v_and_b32_e32 v15, 0xffff0000, v38
	v_and_b32_e32 v25, 0xffff0000, v42
	v_pk_add_f32 v[12:13], v[12:13], v[14:15]
	v_lshlrev_b32_e32 v14, 16, v122
	v_and_b32_e32 v15, 0xffff0000, v122
	v_pk_add_f32 v[14:15], v[24:25], v[14:15]
	v_lshlrev_b32_e32 v16, 16, v31
	v_and_b32_e32 v17, 0xffff0000, v31
	v_lshlrev_b32_e32 v18, 16, v39
	v_and_b32_e32 v19, 0xffff0000, v39
	v_lshlrev_b32_e32 v24, 16, v43
	v_and_b32_e32 v25, 0xffff0000, v43
	v_pk_add_f32 v[12:13], v[12:13], v[14:15]
	v_lshlrev_b32_e32 v14, 16, v123
	v_and_b32_e32 v15, 0xffff0000, v123
	s_waitcnt vmcnt(6)
	v_pk_fma_f32 v[64:65], v[136:137], v[12:13], v[64:65]
	v_pk_add_f32 v[4:5], v[16:17], v[18:19]
	v_pk_add_f32 v[12:13], v[24:25], v[14:15]
	s_waitcnt vmcnt(1)
	v_lshlrev_b32_e32 v14, 16, v156
	v_pk_add_f32 v[4:5], v[4:5], v[12:13]
	v_lshlrev_b32_e32 v12, 16, v148
	v_pk_fma_f32 v[66:67], v[138:139], v[4:5], v[66:67]
	v_lshlrev_b32_e32 v4, 16, v140
	v_and_b32_e32 v5, 0xffff0000, v140
	v_lshlrev_b32_e32 v6, 16, v144
	v_and_b32_e32 v7, 0xffff0000, v144
	v_and_b32_e32 v13, 0xffff0000, v148
	v_and_b32_e32 v15, 0xffff0000, v156
	v_pk_add_f32 v[4:5], v[4:5], v[6:7]
	v_pk_add_f32 v[6:7], v[12:13], v[14:15]
	v_lshlrev_b32_e32 v8, 16, v149
	v_pk_add_f32 v[4:5], v[4:5], v[6:7]
	v_lshlrev_b32_e32 v6, 16, v145
	s_waitcnt vmcnt(0)
	v_pk_fma_f32 v[56:57], v[160:161], v[4:5], v[56:57]
	v_lshlrev_b32_e32 v4, 16, v141
	v_and_b32_e32 v5, 0xffff0000, v141
	v_and_b32_e32 v7, 0xffff0000, v145
	v_and_b32_e32 v9, 0xffff0000, v149
	v_lshlrev_b32_e32 v12, 16, v157
	v_and_b32_e32 v13, 0xffff0000, v157
	v_pk_add_f32 v[4:5], v[4:5], v[6:7]
	v_pk_add_f32 v[6:7], v[8:9], v[12:13]
	v_lshlrev_b32_e32 v8, 16, v150
	v_pk_add_f32 v[4:5], v[4:5], v[6:7]
	v_lshlrev_b32_e32 v6, 16, v146
	v_pk_fma_f32 v[60:61], v[162:163], v[4:5], v[60:61]
	v_lshlrev_b32_e32 v4, 16, v142
	v_and_b32_e32 v5, 0xffff0000, v142
	v_and_b32_e32 v7, 0xffff0000, v146
	v_and_b32_e32 v9, 0xffff0000, v150
	v_lshlrev_b32_e32 v12, 16, v158
	v_and_b32_e32 v13, 0xffff0000, v158
	v_pk_add_f32 v[4:5], v[4:5], v[6:7]
	v_pk_add_f32 v[6:7], v[8:9], v[12:13]
	v_lshlrev_b32_e32 v8, 16, v159
	v_pk_add_f32 v[4:5], v[4:5], v[6:7]
	v_lshlrev_b32_e32 v6, 16, v151
	v_pk_fma_f32 v[58:59], v[152:153], v[4:5], v[58:59]
	v_lshlrev_b32_e32 v0, 16, v143
	v_and_b32_e32 v1, 0xffff0000, v143
	v_lshlrev_b32_e32 v4, 16, v147
	v_and_b32_e32 v5, 0xffff0000, v147
	v_and_b32_e32 v7, 0xffff0000, v151
	v_and_b32_e32 v9, 0xffff0000, v159
	v_pk_add_f32 v[0:1], v[0:1], v[4:5]
	v_pk_add_f32 v[4:5], v[6:7], v[8:9]
	s_nop 0
	v_pk_add_f32 v[0:1], v[0:1], v[4:5]
	s_nop 0
	v_pk_fma_f32 v[62:63], v[154:155], v[0:1], v[62:63]
	s_branch .LBB0_1229
